# GEMM K-loops (all four): per-segment s_setprio flips removed, one static s_setprio 1 for waves 4-7 before each loop, reset to 0 after
# speedup vs baseline: 1.0077x; 1.0077x over previous
; #define PG8_STAGE(bufoff, gbase, voff) do { _Pragma("unroll") for (int _i = 0; _i < 2; ++_i) \
;         __builtin_amdgcn_global_load_lds((const unsigned*)((const char*)(gbase) + (voff)[_i]), (LAS unsigned*)(lds + (bufoff) + ldsw + _i * 8192), 16, 0, 0); } while (0)
; #define PG8_LDA(dst, b, h) do { _Pragma("unroll") for (int m = 0; m < 4; ++m) _Pragma("unroll") for (int k = 0; k < 2; ++k) dst[m][k] = *(const LAS bf16x8*)(lds + PG8_SA(b, h) + aoff + m * 2048 + k * 1024); } while (0)
; #define PG8_WAIT_V(n) asm volatile("s_waitcnt vmcnt(" #n ")" ::: "memory")
; template <class Epi>
; __device__ __forceinline__ void gemm_phase(LAS unsigned char* lds, const Gemm g, const StaticOrder& S, const Epi& E) {
;     ...
;     f32x4 acc[2][2][4][2];
; #pragma unroll
;     for (int a = 0; a < 2; ++a)
; #pragma unroll
;         for (int b = 0; b < 2; ++b)
; #pragma unroll
;             for (int m = 0; m < 4; ++m)
; #pragma unroll
;                 for (int n = 0; n < 2; ++n) acc[a][b][m][n] = (f32x4){0.f, 0.f, 0.f, 0.f};
;     bf16x8 At[4][2], B0[2][2], B1[2][2];
;     const char* cA = (const char*)g.A + (size_t)cur.pm * tstep; const char* cB = (const char*)g.Bt + (size_t)cur.pn * tstep;
;     PG8_STAGE(PG8_SB(0, 0), cB, voffB); PG8_STAGE(PG8_SA(0, 0), cA, voffA); PG8_STAGE(PG8_SB(0, 1), cB + hstep, voffB); PG8_STAGE(PG8_SA(0, 1), cA + hstep, voffA);
;     if (wr == 1) PG8_BAR;
;     PG8_WAIT_V(4); PG8_BAR;
;     PG8_STAGE(PG8_SB(1, 0), cB + kstep, voffB); PG8_STAGE(PG8_SA(1, 0), cA + kstep, voffA); PG8_STAGE(PG8_SB(1, 1), cB + hstep + kstep, voffB);
;     PG8_WAIT_V(6); PG8_BAR;
;     for (;;) {
;         const bool has_next = S.next(ui + 1, nxt);
;         const char* nA = has_next ? (const char*)g.A + (size_t)nxt.pm * tstep : cA; const char* nB = has_next ? (const char*)g.Bt + (size_t)nxt.pn * tstep : cB;
;         for (int t = 0; t < nt; t += 2) {
;             const bool last = (t == nt - 2);
;             const char* a1 = cA + (size_t)(t + 1) * kstep;
;             const char* a2 = last ? nA : cA + (size_t)(t + 2) * kstep; const char* b2 = last ? nB : cB + (size_t)(t + 2) * kstep;
;             const char* a3 = a2 + kstep; const char* b3 = b2 + kstep;
;             PG8_LDB(B0, 0, 0); PG8_SCHED; PG8_LDA(At, 0, 0); PG8_STAGE(PG8_SA(1, 1), a1 + hstep, voffA);
;             PG8_WAIT_L(8); PG8_BAR; PG8_WAIT_L(0); PG8_MMA(0, 0, At, B0); PG8_BAR; PG8_SCHED;
.Lp7_units_done:
	s_add_u32 s44, s18, 0x100
	v_mov_b32_e32 v4, 0
	s_addc_u32 s46, s19, 0
	s_cmp_eq_u32 s40, 1
	s_cselect_b32 s47, -2, 64
	s_waitcnt lgkmcnt(0)
	v_mov_b32_e32 v5, v4
	v_mov_b32_e32 v6, v4
	v_mov_b32_e32 v7, v4
	v_mov_b32_e32 v8, v4
	v_mov_b32_e32 v9, v4
	v_mov_b32_e32 v10, v4
	v_mov_b32_e32 v11, v4
	v_mov_b32_e32 v20, v4
	v_mov_b32_e32 v21, v4
	v_mov_b32_e32 v22, v4
	v_mov_b32_e32 v23, v4
	v_mov_b32_e32 v24, v4
	v_mov_b32_e32 v25, v4
	v_mov_b32_e32 v26, v4
	v_mov_b32_e32 v27, v4
	v_mov_b32_e32 v36, v4
	v_mov_b32_e32 v37, v4
	v_mov_b32_e32 v38, v4
	v_mov_b32_e32 v39, v4
	v_mov_b32_e32 v40, v4
	v_mov_b32_e32 v41, v4
	v_mov_b32_e32 v42, v4
	v_mov_b32_e32 v43, v4
	v_mov_b32_e32 v52, v4
	v_mov_b32_e32 v53, v4
	v_mov_b32_e32 v54, v4
	v_mov_b32_e32 v55, v4
	v_mov_b32_e32 v56, v4
	v_mov_b32_e32 v57, v4
	v_mov_b32_e32 v58, v4
	v_mov_b32_e32 v59, v4
	v_mov_b32_e32 v12, v4
	v_mov_b32_e32 v13, v4
	v_mov_b32_e32 v14, v4
	v_mov_b32_e32 v15, v4
	v_mov_b32_e32 v16, v4
	v_mov_b32_e32 v17, v4
	v_mov_b32_e32 v18, v4
	v_mov_b32_e32 v19, v4
	v_mov_b32_e32 v28, v4
	v_mov_b32_e32 v29, v4
	v_mov_b32_e32 v30, v4
	v_mov_b32_e32 v31, v4
	v_mov_b32_e32 v32, v4
	v_mov_b32_e32 v33, v4
	v_mov_b32_e32 v34, v4
	v_mov_b32_e32 v35, v4
	v_mov_b32_e32 v44, v4
	v_mov_b32_e32 v45, v4
	v_mov_b32_e32 v46, v4
	v_mov_b32_e32 v47, v4
	v_mov_b32_e32 v48, v4
	v_mov_b32_e32 v49, v4
	v_mov_b32_e32 v50, v4
	v_mov_b32_e32 v51, v4
	v_mov_b32_e32 v60, v4
	v_mov_b32_e32 v61, v4
	v_mov_b32_e32 v62, v4
	v_mov_b32_e32 v63, v4
	v_mov_b32_e32 v64, v4
	v_mov_b32_e32 v65, v4
	v_mov_b32_e32 v66, v4
	v_mov_b32_e32 v67, v4
	v_mov_b32_e32 v68, v4
	v_mov_b32_e32 v69, v4
	v_mov_b32_e32 v70, v4
	v_mov_b32_e32 v71, v4
	v_mov_b32_e32 v72, v4
	v_mov_b32_e32 v73, v4
	v_mov_b32_e32 v74, v4
	v_mov_b32_e32 v75, v4
	v_mov_b32_e32 v84, v4
	v_mov_b32_e32 v85, v4
	v_mov_b32_e32 v86, v4
	v_mov_b32_e32 v87, v4
	v_mov_b32_e32 v88, v4
	v_mov_b32_e32 v89, v4
	v_mov_b32_e32 v90, v4
	v_mov_b32_e32 v91, v4
	v_mov_b32_e32 v100, v4
	v_mov_b32_e32 v101, v4
	v_mov_b32_e32 v102, v4
	v_mov_b32_e32 v103, v4
	v_mov_b32_e32 v104, v4
	v_mov_b32_e32 v105, v4
	v_mov_b32_e32 v106, v4
	v_mov_b32_e32 v107, v4
	v_mov_b32_e32 v116, v4
	v_mov_b32_e32 v117, v4
	v_mov_b32_e32 v118, v4
	v_mov_b32_e32 v119, v4
	v_mov_b32_e32 v120, v4
	v_mov_b32_e32 v121, v4
	v_mov_b32_e32 v122, v4
	v_mov_b32_e32 v123, v4
	v_mov_b32_e32 v76, v4
	v_mov_b32_e32 v77, v4
	v_mov_b32_e32 v78, v4
	v_mov_b32_e32 v79, v4
	v_mov_b32_e32 v80, v4
	v_mov_b32_e32 v81, v4
	v_mov_b32_e32 v82, v4
	v_mov_b32_e32 v83, v4
	v_mov_b32_e32 v92, v4
	v_mov_b32_e32 v93, v4
	v_mov_b32_e32 v94, v4
	v_mov_b32_e32 v95, v4
	v_mov_b32_e32 v96, v4
	v_mov_b32_e32 v97, v4
	v_mov_b32_e32 v98, v4
	v_mov_b32_e32 v99, v4
	v_mov_b32_e32 v108, v4
	v_mov_b32_e32 v109, v4
	v_mov_b32_e32 v110, v4
	v_mov_b32_e32 v111, v4
	v_mov_b32_e32 v112, v4
	v_mov_b32_e32 v113, v4
	v_mov_b32_e32 v114, v4
	v_mov_b32_e32 v115, v4
	v_mov_b32_e32 v124, v4
	v_mov_b32_e32 v125, v4
	v_mov_b32_e32 v126, v4
	v_mov_b32_e32 v127, v4
	v_mov_b32_e32 v128, v4
	v_mov_b32_e32 v129, v4
	v_mov_b32_e32 v130, v4
	v_mov_b32_e32 v131, v4
	v_readfirstlane_b32 s98, v151
	s_nop 3
	s_lshr_b32 s98, s98, 8
	s_cmp_lg_u32 s98, 0
	s_cbranch_scc0 .Lprio_skip_23
	s_setprio 1
.Lprio_skip_23:
.LBB0_23:
	s_add_u32 s6, s16, 0x100
	s_addc_u32 s7, s17, 0
	s_add_i32 s48, 0, 0x10000
	v_add_u32_e32 v178, s48, v147
	ds_read_b128 v[142:145], v178
	ds_read_b128 v[170:173], v178 offset:1024
	ds_read_b128 v[174:177], v178 offset:2048
	ds_read_b128 v[178:181], v178 offset:3072
	s_cmpk_eq_i32 s47, 0x54
	s_cselect_b32 s21, s15, s7
	s_cselect_b32 s20, s14, s6
	s_cselect_b32 s19, s1, s46
	s_cselect_b32 s18, s0, s44
	v_lshl_add_u64 v[226:227], s[16:17], 0, v[138:139]
	s_add_i32 m0, s31, 0xc000
	ds_read_b128 v[182:185], v163
	ds_read_b128 v[186:189], v163 offset:1024
	ds_read_b128 v[190:193], v163 offset:2048
	ds_read_b128 v[194:197], v163 offset:3072
	ds_read_b128 v[198:201], v163 offset:4096
	ds_read_b128 v[214:217], v163 offset:5120
	ds_read_b128 v[218:221], v163 offset:6144
	ds_read_b128 v[222:225], v163 offset:7168
	global_load_lds_dwordx4 v[226:227], off
	v_lshl_add_u64 v[226:227], s[16:17], 0, v[140:141]
	s_add_i32 m0, s31, 0xe000
	s_nop 0
	global_load_lds_dwordx4 v[226:227], off
	s_waitcnt lgkmcnt(8)
	s_barrier
	s_waitcnt lgkmcnt(0)
	s_waitcnt lgkmcnt(0)
	v_mfma_f32_16x16x32_bf16 v[128:131], v[142:145], v[182:185], v[128:131]
	v_mfma_f32_16x16x32_bf16 v[124:127], v[174:177], v[182:185], v[124:127]
	v_mfma_f32_16x16x32_bf16 v[112:115], v[142:145], v[190:193], v[112:115]
	v_mfma_f32_16x16x32_bf16 v[108:111], v[174:177], v[190:193], v[108:111]
	v_mfma_f32_16x16x32_bf16 v[96:99], v[142:145], v[198:201], v[96:99]
	v_mfma_f32_16x16x32_bf16 v[92:95], v[174:177], v[198:201], v[92:95]
	v_mfma_f32_16x16x32_bf16 v[80:83], v[142:145], v[218:221], v[80:83]
	v_mfma_f32_16x16x32_bf16 v[76:79], v[174:177], v[218:221], v[76:79]
	v_mfma_f32_16x16x32_bf16 v[128:131], v[170:173], v[186:189], v[128:131]
	v_mfma_f32_16x16x32_bf16 v[124:127], v[178:181], v[186:189], v[124:127]
	v_mfma_f32_16x16x32_bf16 v[112:115], v[170:173], v[194:197], v[112:115]
	v_mfma_f32_16x16x32_bf16 v[108:111], v[178:181], v[194:197], v[108:111]
	v_mfma_f32_16x16x32_bf16 v[96:99], v[170:173], v[214:217], v[96:99]
	v_mfma_f32_16x16x32_bf16 v[92:95], v[178:181], v[214:217], v[92:95]
	v_mfma_f32_16x16x32_bf16 v[80:83], v[170:173], v[222:225], v[80:83]
	v_mfma_f32_16x16x32_bf16 v[76:79], v[178:181], v[222:225], v[76:79]
	s_barrier
; #define PG8_STAGE(bufoff, gbase, voff) do { _Pragma("unroll") for (int _i = 0; _i < 2; ++_i) \
;         __builtin_amdgcn_global_load_lds((const unsigned*)((const char*)(gbase) + (voff)[_i]), (LAS unsigned*)(lds + (bufoff) + ldsw + _i * 8192), 16, 0, 0); } while (0)
; #define PG8_LDA(dst, b, h) do { _Pragma("unroll") for (int m = 0; m < 4; ++m) _Pragma("unroll") for (int k = 0; k < 2; ++k) dst[m][k] = *(const LAS bf16x8*)(lds + PG8_SA(b, h) + aoff + m * 2048 + k * 1024); } while (0)
; #define PG8_LDB(dst, b, h) do { _Pragma("unroll") for (int n = 0; n < 2; ++n) _Pragma("unroll") for (int k = 0; k < 2; ++k) dst[n][k] = *(const LAS bf16x8*)(lds + PG8_SB(b, h) + boff + n * 2048 + k * 1024); } while (0)
; #define PG8_MMA(ai, bj, At, Bt) do { __builtin_amdgcn_s_setprio(1); _Pragma("unroll") for (int m = 0; m < 4; ++m) _Pragma("unroll") for (int n = 0; n < 2; ++n) _Pragma("unroll") for (int k = 0; k < 2; ++k) \
;         acc[ai][bj][m][n] = __builtin_amdgcn_mfma_f32_16x16x32_bf16(Bt[n][k], At[m][k], acc[ai][bj][m][n], 0, 0, 0); __builtin_amdgcn_s_setprio(0); } while (0)
; #define PG8_WAIT_V(n) asm volatile("s_waitcnt vmcnt(" #n ")" ::: "memory")
; #define PG8_WAIT_L(n) asm volatile("s_waitcnt lgkmcnt(" #n ")" ::: "memory")
; #define PG8_BAR __builtin_amdgcn_s_barrier()
; #define PG8_SCHED __builtin_amdgcn_sched_barrier(0)
; template <class Epi>
; __device__ __forceinline__ void gemm_phase(LAS unsigned char* lds, const Gemm g, const StaticOrder& S, const Epi& E) {
;     ...
;             PG8_LDB(B1, 0, 1); PG8_STAGE(PG8_SB(0, 0), b2, voffB);
;             PG8_BAR; PG8_WAIT_L(0); PG8_MMA(0, 1, At, B1); PG8_BAR;
;             PG8_LDA(At, 0, 1); PG8_STAGE(PG8_SA(0, 0), a2, voffA);
;             PG8_BAR; PG8_WAIT_L(0); PG8_MMA(1, 0, At, B0); PG8_BAR; PG8_SCHED;
;             PG8_STAGE(PG8_SB(0, 1), b2 + hstep, voffB);
;             PG8_WAIT_V(6); PG8_BAR; PG8_MMA(1, 1, At, B1); PG8_BAR;
;             PG8_LDB(B0, 1, 0); PG8_SCHED; PG8_LDA(At, 1, 0); PG8_STAGE(PG8_SA(0, 1), a2 + hstep, voffA);
;             PG8_WAIT_L(8); PG8_BAR; PG8_WAIT_L(0); PG8_MMA(0, 0, At, B0); PG8_BAR; PG8_SCHED;
	s_add_i32 s52, 0, 0x14000
	s_add_i32 s16, s48, s30
	v_add_u32_e32 v238, s52, v147
	v_lshl_add_u64 v[242:243], s[18:19], 0, v[148:149]
	s_mov_b32 m0, s16
	ds_read_b128 v[226:229], v238
	ds_read_b128 v[230:233], v238 offset:1024
	ds_read_b128 v[234:237], v238 offset:2048
	ds_read_b128 v[238:241], v238 offset:3072
	global_load_lds_dwordx4 v[242:243], off
	v_lshl_add_u64 v[244:245], s[18:19], 0, v[136:137]
	s_add_i32 m0, s16, 0x2000
	s_nop 0
	global_load_lds_dwordx4 v[244:245], off
	s_barrier
	s_waitcnt lgkmcnt(0)
	s_waitcnt lgkmcnt(0)
	v_mfma_f32_16x16x32_bf16 v[120:123], v[226:229], v[182:185], v[120:123]
	v_mfma_f32_16x16x32_bf16 v[116:119], v[234:237], v[182:185], v[116:119]
	v_mfma_f32_16x16x32_bf16 v[104:107], v[226:229], v[190:193], v[104:107]
	v_mfma_f32_16x16x32_bf16 v[100:103], v[234:237], v[190:193], v[100:103]
	v_mfma_f32_16x16x32_bf16 v[88:91], v[226:229], v[198:201], v[88:91]
	v_mfma_f32_16x16x32_bf16 v[84:87], v[234:237], v[198:201], v[84:87]
	v_mfma_f32_16x16x32_bf16 v[72:75], v[226:229], v[218:221], v[72:75]
	v_mfma_f32_16x16x32_bf16 v[68:71], v[234:237], v[218:221], v[68:71]
	v_mfma_f32_16x16x32_bf16 v[120:123], v[230:233], v[186:189], v[120:123]
	v_mfma_f32_16x16x32_bf16 v[116:119], v[238:241], v[186:189], v[116:119]
	v_mfma_f32_16x16x32_bf16 v[104:107], v[230:233], v[194:197], v[104:107]
	v_mfma_f32_16x16x32_bf16 v[100:103], v[238:241], v[194:197], v[100:103]
	v_mfma_f32_16x16x32_bf16 v[88:91], v[230:233], v[214:217], v[88:91]
	v_mfma_f32_16x16x32_bf16 v[84:87], v[238:241], v[214:217], v[84:87]
	v_mfma_f32_16x16x32_bf16 v[72:75], v[230:233], v[222:225], v[72:75]
	v_mfma_f32_16x16x32_bf16 v[68:71], v[238:241], v[222:225], v[68:71]
	s_mov_b32 m0, s31
	v_lshl_add_u64 v[246:247], s[20:21], 0, v[132:133]
	s_barrier
	ds_read_b128 v[182:185], v163 offset:16384
	ds_read_b128 v[186:189], v163 offset:17408
	ds_read_b128 v[190:193], v163 offset:18432
	ds_read_b128 v[194:197], v163 offset:19456
	ds_read_b128 v[198:201], v163 offset:20480
	ds_read_b128 v[214:217], v163 offset:21504
	ds_read_b128 v[218:221], v163 offset:22528
	ds_read_b128 v[222:225], v163 offset:23552
	global_load_lds_dwordx4 v[246:247], off
	v_lshl_add_u64 v[248:249], s[20:21], 0, v[134:135]
	s_mov_b32 m0, s33
	s_nop 0
	global_load_lds_dwordx4 v[248:249], off
	s_barrier
	s_waitcnt lgkmcnt(0)
	s_waitcnt lgkmcnt(0)
	v_mfma_f32_16x16x32_bf16 v[64:67], v[142:145], v[182:185], v[64:67]
	v_mfma_f32_16x16x32_bf16 v[60:63], v[174:177], v[182:185], v[60:63]
	v_mfma_f32_16x16x32_bf16 v[48:51], v[142:145], v[190:193], v[48:51]
	v_mfma_f32_16x16x32_bf16 v[44:47], v[174:177], v[190:193], v[44:47]
	v_mfma_f32_16x16x32_bf16 v[32:35], v[142:145], v[198:201], v[32:35]
	v_mfma_f32_16x16x32_bf16 v[28:31], v[174:177], v[198:201], v[28:31]
	v_mfma_f32_16x16x32_bf16 v[16:19], v[142:145], v[218:221], v[16:19]
	v_mfma_f32_16x16x32_bf16 v[12:15], v[174:177], v[218:221], v[12:15]
	v_mfma_f32_16x16x32_bf16 v[64:67], v[170:173], v[186:189], v[64:67]
	v_mfma_f32_16x16x32_bf16 v[60:63], v[178:181], v[186:189], v[60:63]
	v_mfma_f32_16x16x32_bf16 v[48:51], v[170:173], v[194:197], v[48:51]
	v_mfma_f32_16x16x32_bf16 v[44:47], v[178:181], v[194:197], v[44:47]
	v_mfma_f32_16x16x32_bf16 v[32:35], v[170:173], v[214:217], v[32:35]
	v_mfma_f32_16x16x32_bf16 v[28:31], v[178:181], v[214:217], v[28:31]
	v_mfma_f32_16x16x32_bf16 v[16:19], v[170:173], v[222:225], v[16:19]
	v_mfma_f32_16x16x32_bf16 v[12:15], v[178:181], v[222:225], v[12:15]
	s_barrier
	s_add_u32 s16, s18, 0x160000
	s_addc_u32 s17, s19, 0
	s_add_i32 s48, s52, s30
	v_lshl_add_u64 v[142:143], s[16:17], 0, v[148:149]
	s_mov_b32 m0, s48
	s_nop 0
	global_load_lds_dwordx4 v[142:143], off
	v_lshl_add_u64 v[142:143], s[16:17], 0, v[136:137]
	s_add_i32 m0, s48, 0x2000
	s_nop 0
	global_load_lds_dwordx4 v[142:143], off
	s_waitcnt vmcnt(6)
	s_barrier
	v_mfma_f32_16x16x32_bf16 v[56:59], v[226:229], v[182:185], v[56:59]
	v_mfma_f32_16x16x32_bf16 v[52:55], v[234:237], v[182:185], v[52:55]
	v_mfma_f32_16x16x32_bf16 v[40:43], v[226:229], v[190:193], v[40:43]
	v_mfma_f32_16x16x32_bf16 v[36:39], v[234:237], v[190:193], v[36:39]
	v_mfma_f32_16x16x32_bf16 v[24:27], v[226:229], v[198:201], v[24:27]
	v_mfma_f32_16x16x32_bf16 v[20:23], v[234:237], v[198:201], v[20:23]
	v_mfma_f32_16x16x32_bf16 v[8:11], v[226:229], v[218:221], v[8:11]
	v_mfma_f32_16x16x32_bf16 v[4:7], v[234:237], v[218:221], v[4:7]
	v_mfma_f32_16x16x32_bf16 v[56:59], v[230:233], v[186:189], v[56:59]
	v_mfma_f32_16x16x32_bf16 v[52:55], v[238:241], v[186:189], v[52:55]
	v_mfma_f32_16x16x32_bf16 v[40:43], v[230:233], v[194:197], v[40:43]
	v_mfma_f32_16x16x32_bf16 v[36:39], v[238:241], v[194:197], v[36:39]
	v_mfma_f32_16x16x32_bf16 v[24:27], v[230:233], v[214:217], v[24:27]
	v_mfma_f32_16x16x32_bf16 v[20:23], v[238:241], v[214:217], v[20:23]
	v_mfma_f32_16x16x32_bf16 v[8:11], v[230:233], v[222:225], v[8:11]
	v_mfma_f32_16x16x32_bf16 v[4:7], v[238:241], v[222:225], v[4:7]
	s_add_i32 s48, 0, 0x18000
	v_add_u32_e32 v178, s48, v147
	s_barrier
	ds_read_b128 v[142:145], v178
	ds_read_b128 v[170:173], v178 offset:1024
	ds_read_b128 v[174:177], v178 offset:2048
	ds_read_b128 v[178:181], v178 offset:3072
	s_add_u32 s16, s20, 0x160000
	s_addc_u32 s17, s21, 0
	s_mov_b32 m0, s36
	v_lshl_add_u64 v[226:227], s[16:17], 0, v[132:133]
	ds_read_b128 v[182:185], v163 offset:32768
	ds_read_b128 v[186:189], v163 offset:33792
	ds_read_b128 v[190:193], v163 offset:34816
	ds_read_b128 v[194:197], v163 offset:35840
	ds_read_b128 v[198:201], v163 offset:36864
	ds_read_b128 v[214:217], v163 offset:37888
	ds_read_b128 v[218:221], v163 offset:38912
	ds_read_b128 v[222:225], v163 offset:39936
	global_load_lds_dwordx4 v[226:227], off
	v_lshl_add_u64 v[226:227], s[16:17], 0, v[134:135]
	s_mov_b32 m0, s37
	s_nop 0
	global_load_lds_dwordx4 v[226:227], off
	s_waitcnt lgkmcnt(8)
	s_barrier
; #define PG8_STAGE(bufoff, gbase, voff) do { _Pragma("unroll") for (int _i = 0; _i < 2; ++_i) \
;         __builtin_amdgcn_global_load_lds((const unsigned*)((const char*)(gbase) + (voff)[_i]), (LAS unsigned*)(lds + (bufoff) + ldsw + _i * 8192), 16, 0, 0); } while (0)
; #define PG8_LDA(dst, b, h) do { _Pragma("unroll") for (int m = 0; m < 4; ++m) _Pragma("unroll") for (int k = 0; k < 2; ++k) dst[m][k] = *(const LAS bf16x8*)(lds + PG8_SA(b, h) + aoff + m * 2048 + k * 1024); } while (0)
; #define PG8_LDB(dst, b, h) do { _Pragma("unroll") for (int n = 0; n < 2; ++n) _Pragma("unroll") for (int k = 0; k < 2; ++k) dst[n][k] = *(const LAS bf16x8*)(lds + PG8_SB(b, h) + boff + n * 2048 + k * 1024); } while (0)
; #define PG8_MMA(ai, bj, At, Bt) do { __builtin_amdgcn_s_setprio(1); _Pragma("unroll") for (int m = 0; m < 4; ++m) _Pragma("unroll") for (int n = 0; n < 2; ++n) _Pragma("unroll") for (int k = 0; k < 2; ++k) \
;         acc[ai][bj][m][n] = __builtin_amdgcn_mfma_f32_16x16x32_bf16(Bt[n][k], At[m][k], acc[ai][bj][m][n], 0, 0, 0); __builtin_amdgcn_s_setprio(0); } while (0)
; #define PG8_WAIT_L(n) asm volatile("s_waitcnt lgkmcnt(" #n ")" ::: "memory")
; #define PG8_BAR __builtin_amdgcn_s_barrier()
; #define PG8_SCHED __builtin_amdgcn_sched_barrier(0)
; template <class Epi>
; __device__ __forceinline__ void gemm_phase(LAS unsigned char* lds, const Gemm g, const StaticOrder& S, const Epi& E) {
;     ...
;             PG8_WAIT_L(8); PG8_BAR; PG8_WAIT_L(0); PG8_MMA(0, 0, At, B0); PG8_BAR; PG8_SCHED;
;             PG8_LDB(B1, 1, 1); PG8_STAGE(PG8_SB(1, 0), b3, voffB);
;             PG8_BAR; PG8_WAIT_L(0); PG8_MMA(0, 1, At, B1); PG8_BAR;
;             PG8_LDA(At, 1, 1); PG8_STAGE(PG8_SA(1, 0), a3, voffA);
;             PG8_BAR; PG8_WAIT_L(0); PG8_MMA(1, 0, At, B0); PG8_BAR; PG8_SCHED;
	s_waitcnt lgkmcnt(0)
	s_waitcnt lgkmcnt(0)
	v_mfma_f32_16x16x32_bf16 v[128:131], v[142:145], v[182:185], v[128:131]
	v_mfma_f32_16x16x32_bf16 v[124:127], v[174:177], v[182:185], v[124:127]
	v_mfma_f32_16x16x32_bf16 v[112:115], v[142:145], v[190:193], v[112:115]
	v_mfma_f32_16x16x32_bf16 v[108:111], v[174:177], v[190:193], v[108:111]
	v_mfma_f32_16x16x32_bf16 v[96:99], v[142:145], v[198:201], v[96:99]
	v_mfma_f32_16x16x32_bf16 v[92:95], v[174:177], v[198:201], v[92:95]
	v_mfma_f32_16x16x32_bf16 v[80:83], v[142:145], v[218:221], v[80:83]
	v_mfma_f32_16x16x32_bf16 v[76:79], v[174:177], v[218:221], v[76:79]
	v_mfma_f32_16x16x32_bf16 v[128:131], v[170:173], v[186:189], v[128:131]
	v_mfma_f32_16x16x32_bf16 v[124:127], v[178:181], v[186:189], v[124:127]
	v_mfma_f32_16x16x32_bf16 v[112:115], v[170:173], v[194:197], v[112:115]
	v_mfma_f32_16x16x32_bf16 v[108:111], v[178:181], v[194:197], v[108:111]
	v_mfma_f32_16x16x32_bf16 v[96:99], v[170:173], v[214:217], v[96:99]
	v_mfma_f32_16x16x32_bf16 v[92:95], v[178:181], v[214:217], v[92:95]
	v_mfma_f32_16x16x32_bf16 v[80:83], v[170:173], v[222:225], v[80:83]
	v_mfma_f32_16x16x32_bf16 v[76:79], v[178:181], v[222:225], v[76:79]
	s_barrier
	s_add_i32 s20, 0, 0x1c000
	s_add_i32 s16, s48, s30
	v_add_u32_e32 v238, s20, v147
	v_lshl_add_u64 v[242:243], v[242:243], 0, s[34:35]
	s_mov_b32 m0, s16
	ds_read_b128 v[226:229], v238
	ds_read_b128 v[230:233], v238 offset:1024
	ds_read_b128 v[234:237], v238 offset:2048
	ds_read_b128 v[238:241], v238 offset:3072
	global_load_lds_dwordx4 v[242:243], off
	v_lshl_add_u64 v[242:243], v[244:245], 0, s[34:35]
	s_add_i32 m0, s16, 0x2000
	s_nop 0
	global_load_lds_dwordx4 v[242:243], off
	s_barrier
	s_waitcnt lgkmcnt(0)
	s_waitcnt lgkmcnt(0)
	v_mfma_f32_16x16x32_bf16 v[120:123], v[226:229], v[182:185], v[120:123]
	v_mfma_f32_16x16x32_bf16 v[116:119], v[234:237], v[182:185], v[116:119]
	v_mfma_f32_16x16x32_bf16 v[104:107], v[226:229], v[190:193], v[104:107]
	v_mfma_f32_16x16x32_bf16 v[100:103], v[234:237], v[190:193], v[100:103]
	v_mfma_f32_16x16x32_bf16 v[88:91], v[226:229], v[198:201], v[88:91]
	v_mfma_f32_16x16x32_bf16 v[84:87], v[234:237], v[198:201], v[84:87]
	v_mfma_f32_16x16x32_bf16 v[72:75], v[226:229], v[218:221], v[72:75]
	v_mfma_f32_16x16x32_bf16 v[68:71], v[234:237], v[218:221], v[68:71]
	v_mfma_f32_16x16x32_bf16 v[120:123], v[230:233], v[186:189], v[120:123]
	v_mfma_f32_16x16x32_bf16 v[116:119], v[238:241], v[186:189], v[116:119]
	v_mfma_f32_16x16x32_bf16 v[104:107], v[230:233], v[194:197], v[104:107]
	v_mfma_f32_16x16x32_bf16 v[100:103], v[238:241], v[194:197], v[100:103]
	v_mfma_f32_16x16x32_bf16 v[88:91], v[230:233], v[214:217], v[88:91]
	v_mfma_f32_16x16x32_bf16 v[84:87], v[238:241], v[214:217], v[84:87]
	v_mfma_f32_16x16x32_bf16 v[72:75], v[230:233], v[222:225], v[72:75]
	v_mfma_f32_16x16x32_bf16 v[68:71], v[238:241], v[222:225], v[68:71]
	s_mov_b32 m0, s38
	v_lshl_add_u64 v[242:243], v[246:247], 0, s[34:35]
	s_barrier
	ds_read_b128 v[182:185], v163 offset:49152
	ds_read_b128 v[186:189], v163 offset:50176
	ds_read_b128 v[190:193], v163 offset:51200
	ds_read_b128 v[194:197], v163 offset:52224
	ds_read_b128 v[198:201], v163 offset:53248
	ds_read_b128 v[214:217], v163 offset:54272
	ds_read_b128 v[218:221], v163 offset:55296
	ds_read_b128 v[222:225], v163 offset:56320
	global_load_lds_dwordx4 v[242:243], off
	v_lshl_add_u64 v[242:243], v[248:249], 0, s[34:35]
	s_mov_b32 m0, s39
	s_nop 0
	global_load_lds_dwordx4 v[242:243], off
	s_barrier
	s_waitcnt lgkmcnt(0)
	s_waitcnt lgkmcnt(0)
	v_mfma_f32_16x16x32_bf16 v[64:67], v[142:145], v[182:185], v[64:67]
	v_mfma_f32_16x16x32_bf16 v[60:63], v[174:177], v[182:185], v[60:63]
	v_mfma_f32_16x16x32_bf16 v[48:51], v[142:145], v[190:193], v[48:51]
	v_mfma_f32_16x16x32_bf16 v[44:47], v[174:177], v[190:193], v[44:47]
	v_mfma_f32_16x16x32_bf16 v[32:35], v[142:145], v[198:201], v[32:35]
	v_mfma_f32_16x16x32_bf16 v[28:31], v[174:177], v[198:201], v[28:31]
	v_mfma_f32_16x16x32_bf16 v[16:19], v[142:145], v[218:221], v[16:19]
	v_mfma_f32_16x16x32_bf16 v[12:15], v[174:177], v[218:221], v[12:15]
	v_mfma_f32_16x16x32_bf16 v[64:67], v[170:173], v[186:189], v[64:67]
	v_mfma_f32_16x16x32_bf16 v[60:63], v[178:181], v[186:189], v[60:63]
	v_mfma_f32_16x16x32_bf16 v[48:51], v[170:173], v[194:197], v[48:51]
	v_mfma_f32_16x16x32_bf16 v[44:47], v[178:181], v[194:197], v[44:47]
	v_mfma_f32_16x16x32_bf16 v[32:35], v[170:173], v[214:217], v[32:35]
	v_mfma_f32_16x16x32_bf16 v[28:31], v[178:181], v[214:217], v[28:31]
	v_mfma_f32_16x16x32_bf16 v[16:19], v[170:173], v[222:225], v[16:19]
	v_mfma_f32_16x16x32_bf16 v[12:15], v[178:181], v[222:225], v[12:15]
	s_barrier
; #define PG8_STAGE(bufoff, gbase, voff) do { _Pragma("unroll") for (int _i = 0; _i < 2; ++_i) \
;         __builtin_amdgcn_global_load_lds((const unsigned*)((const char*)(gbase) + (voff)[_i]), (LAS unsigned*)(lds + (bufoff) + ldsw + _i * 8192), 16, 0, 0); } while (0)
; #define PG8_MMA(ai, bj, At, Bt) do { __builtin_amdgcn_s_setprio(1); _Pragma("unroll") for (int m = 0; m < 4; ++m) _Pragma("unroll") for (int n = 0; n < 2; ++n) _Pragma("unroll") for (int k = 0; k < 2; ++k) \
;         acc[ai][bj][m][n] = __builtin_amdgcn_mfma_f32_16x16x32_bf16(Bt[n][k], At[m][k], acc[ai][bj][m][n], 0, 0, 0); __builtin_amdgcn_s_setprio(0); } while (0)
; #define PG8_WAIT_V(n) asm volatile("s_waitcnt vmcnt(" #n ")" ::: "memory")
; #define PG8_BAR __builtin_amdgcn_s_barrier()
; template <class Epi>
; __device__ __forceinline__ void gemm_phase(LAS unsigned char* lds, const Gemm g, const StaticOrder& S, const Epi& E) {
;     ...
;             PG8_STAGE(PG8_SB(1, 1), b3 + hstep, voffB);
;             PG8_WAIT_V(6); PG8_BAR; PG8_MMA(1, 1, At, B1); PG8_BAR;
;     __device__ __forceinline__ void operator()(const AccT& acc, const pg8::Unit& u, int wr, int wc, int fr, int fq) const {
;     ...
;                 const int row = row0 + ai * 128 + m * 16;
;                 if (row < NOUTROWS) {
;                     float ss = 0.f;
; #pragma unroll
;                     for (int bj = 0; bj < 2; ++bj) {
;                         const f32x4 v0 = acc[ai][bj][m][0] + __builtin_nontemporal_load((const f32x4*)(H1 + (size_t)row * DM + col0 + bj * 128));
;                         const f32x4 v1 = acc[ai][bj][m][1] + __builtin_nontemporal_load((const f32x4*)(H1 + (size_t)row * DM + col0 + bj * 128 + 4));
;                         *(f32x4*)(out + (size_t)row * DM + col0 + bj * 128) = v0; *(f32x4*)(out + (size_t)row * DM + col0 + bj * 128 + 4) = v1;
;                         ss += v0[0] * v0[0] + v0[1] * v0[1] + v0[2] * v0[2] + v0[3] * v0[3] + v1[0] * v1[0] + v1[1] * v1[1] + v1[2] * v1[2] + v1[3] * v1[3];
;                     }
;                     ss += __shfl_xor(ss, 16); ss += __shfl_xor(ss, 32);
;                     if (fq == 0) atomicAdd(SS3 + row, ss);
	s_add_u32 s16, s18, 0x160080
	s_addc_u32 s17, s19, 0
	s_add_i32 s18, s20, s30
	v_lshl_add_u64 v[142:143], s[16:17], 0, v[148:149]
	s_mov_b32 m0, s18
	s_nop 0
	global_load_lds_dwordx4 v[142:143], off
	v_lshl_add_u64 v[142:143], s[16:17], 0, v[136:137]
	s_add_i32 m0, s18, 0x2000
	s_nop 0
	global_load_lds_dwordx4 v[142:143], off
	s_waitcnt vmcnt(6)
	s_barrier
	v_mfma_f32_16x16x32_bf16 v[56:59], v[226:229], v[182:185], v[56:59]
	v_mfma_f32_16x16x32_bf16 v[52:55], v[234:237], v[182:185], v[52:55]
	v_mfma_f32_16x16x32_bf16 v[40:43], v[226:229], v[190:193], v[40:43]
	v_mfma_f32_16x16x32_bf16 v[36:39], v[234:237], v[190:193], v[36:39]
	v_mfma_f32_16x16x32_bf16 v[24:27], v[226:229], v[198:201], v[24:27]
	v_mfma_f32_16x16x32_bf16 v[20:23], v[234:237], v[198:201], v[20:23]
	v_mfma_f32_16x16x32_bf16 v[8:11], v[226:229], v[218:221], v[8:11]
	v_mfma_f32_16x16x32_bf16 v[4:7], v[234:237], v[218:221], v[4:7]
	v_mfma_f32_16x16x32_bf16 v[56:59], v[230:233], v[186:189], v[56:59]
	v_mfma_f32_16x16x32_bf16 v[52:55], v[238:241], v[186:189], v[52:55]
	v_mfma_f32_16x16x32_bf16 v[40:43], v[230:233], v[194:197], v[40:43]
	v_mfma_f32_16x16x32_bf16 v[36:39], v[238:241], v[194:197], v[36:39]
	v_mfma_f32_16x16x32_bf16 v[24:27], v[230:233], v[214:217], v[24:27]
	v_mfma_f32_16x16x32_bf16 v[20:23], v[238:241], v[214:217], v[20:23]
	v_mfma_f32_16x16x32_bf16 v[8:11], v[230:233], v[222:225], v[8:11]
	v_mfma_f32_16x16x32_bf16 v[4:7], v[238:241], v[222:225], v[4:7]
	s_add_i32 s47, s47, 2
	s_add_u32 s44, s44, 0x100
	s_addc_u32 s46, s46, 0
	s_cmpk_gt_u32 s47, 0x55
	s_mov_b64 s[16:17], s[6:7]
	s_barrier
	s_cbranch_scc0 .LBB0_23
	s_setprio 0
	s_cmp_eq_u32 s40, 2
	s_cbranch_scc1 .Lp7_partial_epilogue
	s_movk_i32 s6, 0x2400
	v_lshl_or_b32 v142, s42, 8, v153
	v_lshl_add_u32 v144, s43, 8, v146
	v_ashrrev_i32_e32 v143, 31, v142
	v_cmp_gt_i32_e32 vcc, s6, v144
	v_lshlrev_b64 v[142:143], 2, v[142:143]
	s_and_saveexec_b64 s[6:7], vcc
	s_cbranch_execz .LBB0_27
	v_ashrrev_i32_e32 v145, 31, v144
	v_lshlrev_b64 v[178:179], 13, v[144:145]
	v_lshl_add_u64 v[170:171], s[2:3], 0, v[178:179]
	v_lshl_add_u64 v[180:181], v[170:171], 0, v[142:143]
	global_load_dwordx4 v[170:173], v[180:181], off nt
	global_load_dwordx4 v[174:177], v[180:181], off offset:16 nt
	v_readlane_b32 s16, v255, 31
	v_readlane_b32 s17, v255, 32
	s_waitcnt vmcnt(0)
	v_pk_add_f32 v[130:131], v[130:131], v[172:173]
	v_lshl_add_u64 v[178:179], s[16:17], 0, v[178:179]
	v_lshl_add_u64 v[178:179], v[178:179], 0, v[142:143]
	v_pk_add_f32 v[128:129], v[128:129], v[170:171]
	v_pk_add_f32 v[126:127], v[126:127], v[176:177]
	v_pk_add_f32 v[124:125], v[124:125], v[174:175]
	global_store_dwordx4 v[178:179], v[128:131], off
	global_store_dwordx4 v[178:179], v[124:127], off offset:16
	global_load_dwordx4 v[170:173], v[180:181], off offset:512 nt
	global_load_dwordx4 v[174:177], v[180:181], off offset:528 nt
	v_mul_f32_e32 v129, v129, v129
	v_fmac_f32_e32 v129, v128, v128
	v_fmac_f32_e32 v129, v130, v130
	v_fmac_f32_e32 v129, v131, v131
	v_fmac_f32_e32 v129, v124, v124
	v_fmac_f32_e32 v129, v125, v125
	v_and_b32_e32 v181, 64, v206
	v_fmac_f32_e32 v129, v126, v126
	v_xor_b32_e32 v180, 16, v206
	v_add_u32_e32 v181, 64, v181
	v_fmac_f32_e32 v129, v127, v127
	v_cmp_lt_i32_e32 vcc, v180, v181
	s_waitcnt vmcnt(0)
	v_pk_add_f32 v[120:121], v[120:121], v[170:171]
	v_pk_add_f32 v[124:125], v[116:117], v[174:175]
	v_mul_f32_e32 v116, v121, v121
	v_pk_add_f32 v[122:123], v[122:123], v[172:173]
	v_fmac_f32_e32 v116, v120, v120
	v_fmac_f32_e32 v116, v122, v122
	v_fmac_f32_e32 v116, v123, v123
	v_fmac_f32_e32 v116, v124, v124
	v_pk_add_f32 v[126:127], v[118:119], v[176:177]
	v_fmac_f32_e32 v116, v125, v125
	v_fmac_f32_e32 v116, v126, v126
	v_cndmask_b32_e32 v180, v206, v180, vcc
	v_fmac_f32_e32 v116, v127, v127
	v_lshlrev_b32_e32 v180, 2, v180
	v_add_f32_e32 v116, v129, v116
	ds_bpermute_b32 v117, v180, v116
	v_xor_b32_e32 v118, 32, v206
	v_cmp_lt_i32_e32 vcc, v118, v181
	global_store_dwordx4 v[178:179], v[120:123], off offset:512
	global_store_dwordx4 v[178:179], v[124:127], off offset:528
	v_cndmask_b32_e32 v118, v206, v118, vcc
	s_waitcnt lgkmcnt(0)
	v_add_f32_e32 v116, v116, v117
	v_lshlrev_b32_e32 v117, 2, v118
	ds_bpermute_b32 v117, v117, v116
	s_and_b64 exec, exec, s[8:9]
	s_cbranch_execz .LBB0_27
	v_lshl_add_u64 v[118:119], v[144:145], 2, s[12:13]
	s_waitcnt lgkmcnt(0)
	v_add_f32_e32 v116, v116, v117
	global_atomic_add_f32 v[118:119], v116, off

; #define PG8_STAGE(bufoff, gbase, voff) do { _Pragma("unroll") for (int _i = 0; _i < 2; ++_i) \
;         __builtin_amdgcn_global_load_lds((const unsigned*)((const char*)(gbase) + (voff)[_i]), (LAS unsigned*)(lds + (bufoff) + ldsw + _i * 8192), 16, 0, 0); } while (0)
; #define PG8_LDA(dst, b, h) do { _Pragma("unroll") for (int m = 0; m < 4; ++m) _Pragma("unroll") for (int k = 0; k < 2; ++k) dst[m][k] = *(const LAS bf16x8*)(lds + PG8_SA(b, h) + aoff + m * 2048 + k * 1024); } while (0)
; #define PG8_LDB(dst, b, h) do { _Pragma("unroll") for (int n = 0; n < 2; ++n) _Pragma("unroll") for (int k = 0; k < 2; ++k) dst[n][k] = *(const LAS bf16x8*)(lds + PG8_SB(b, h) + boff + n * 2048 + k * 1024); } while (0)
; #define PG8_MMA(ai, bj, At, Bt) do { __builtin_amdgcn_s_setprio(1); _Pragma("unroll") for (int m = 0; m < 4; ++m) _Pragma("unroll") for (int n = 0; n < 2; ++n) _Pragma("unroll") for (int k = 0; k < 2; ++k) \
;         acc[ai][bj][m][n] = __builtin_amdgcn_mfma_f32_16x16x32_bf16(Bt[n][k], At[m][k], acc[ai][bj][m][n], 0, 0, 0); __builtin_amdgcn_s_setprio(0); } while (0)
; #define PG8_BAR __builtin_amdgcn_s_barrier()
; template <class Epi>
; __device__ __forceinline__ void gemm_phase(LAS unsigned char* lds, const Gemm g, const StaticOrder& S, const Epi& E) {
;     ...
;         const bool has_next = S.next(ui + 1, nxt);
;         const char* nA = has_next ? (const char*)g.A + (size_t)nxt.pm * tstep : cA; const char* nB = has_next ? (const char*)g.Bt + (size_t)nxt.pn * tstep : cB;
;         for (int t = 0; t < nt; t += 2) {
;             const bool last = (t == nt - 2);
;             const char* a1 = cA + (size_t)(t + 1) * kstep;
;             const char* a2 = last ? nA : cA + (size_t)(t + 2) * kstep; const char* b2 = last ? nB : cB + (size_t)(t + 2) * kstep;
;             const char* a3 = a2 + kstep; const char* b3 = b2 + kstep;
;             PG8_LDB(B0, 0, 0); PG8_SCHED; PG8_LDA(At, 0, 0); PG8_STAGE(PG8_SA(1, 1), a1 + hstep, voffA);
;             PG8_WAIT_L(8); PG8_BAR; PG8_WAIT_L(0); PG8_MMA(0, 0, At, B0); PG8_BAR; PG8_SCHED;
;     ...
; #pragma unroll
;         for (int a = 0; a < 2; ++a)
; #pragma unroll
;             for (int b = 0; b < 2; ++b)
; #pragma unroll
;                 for (int m = 0; m < 4; ++m)
; #pragma unroll
;                     for (int n = 0; n < 2; ++n) acc[a][b][m][n] = (f32x4){0.f, 0.f, 0.f, 0.f};
;         cur = nxt; cA = nA; cB = nB; ++ui;
.LBB0_97:
	s_ashr_i32 s13, s12, 31
	s_cmp_ge_i32 s14, 0
	s_cselect_b64 vcc, -1, 0
	s_lshl_b64 s[14:15], s[12:13], 20
	s_add_u32 s14, s29, s14
	s_addc_u32 s15, s30, s15
	s_and_b64 s[16:17], vcc, exec
	s_cselect_b32 s13, s15, s21
	s_cselect_b32 s42, s14, s20
	s_ashr_i32 s9, s8, 31
	s_lshl_b64 s[16:17], s[8:9], 20
	s_add_u32 s16, s2, s16
	s_addc_u32 s17, s3, s17
	s_and_b64 s[24:25], vcc, exec
	s_cselect_b32 s9, s17, s23
	s_cselect_b32 s43, s16, s22
	s_add_u32 s20, s20, 0x80080
	s_addc_u32 s21, s21, 0
	s_add_u32 s44, s22, 0x100
	v_mov_b32_e32 v4, 0
	s_addc_u32 s46, s23, 0
	s_mov_b32 s47, -2
	v_mov_b32_e32 v5, v4
	v_mov_b32_e32 v6, v4
	v_mov_b32_e32 v7, v4
	v_mov_b32_e32 v8, v4
	v_mov_b32_e32 v9, v4
	v_mov_b32_e32 v10, v4
	v_mov_b32_e32 v11, v4
	v_mov_b32_e32 v20, v4
	v_mov_b32_e32 v21, v4
	v_mov_b32_e32 v22, v4
	v_mov_b32_e32 v23, v4
	v_mov_b32_e32 v24, v4
	v_mov_b32_e32 v25, v4
	v_mov_b32_e32 v26, v4
	v_mov_b32_e32 v27, v4
	v_mov_b32_e32 v36, v4
	v_mov_b32_e32 v37, v4
	v_mov_b32_e32 v38, v4
	v_mov_b32_e32 v39, v4
	v_mov_b32_e32 v40, v4
	v_mov_b32_e32 v41, v4
	v_mov_b32_e32 v42, v4
	v_mov_b32_e32 v43, v4
	v_mov_b32_e32 v52, v4
	v_mov_b32_e32 v53, v4
	v_mov_b32_e32 v54, v4
	v_mov_b32_e32 v55, v4
	v_mov_b32_e32 v56, v4
	v_mov_b32_e32 v57, v4
	v_mov_b32_e32 v58, v4
	v_mov_b32_e32 v59, v4
	v_mov_b32_e32 v12, v4
	v_mov_b32_e32 v13, v4
	v_mov_b32_e32 v14, v4
	v_mov_b32_e32 v15, v4
	v_mov_b32_e32 v16, v4
	v_mov_b32_e32 v17, v4
	v_mov_b32_e32 v18, v4
	v_mov_b32_e32 v19, v4
	v_mov_b32_e32 v28, v4
	v_mov_b32_e32 v29, v4
	v_mov_b32_e32 v30, v4
	v_mov_b32_e32 v31, v4
	v_mov_b32_e32 v32, v4
	v_mov_b32_e32 v33, v4
	v_mov_b32_e32 v34, v4
	v_mov_b32_e32 v35, v4
	v_mov_b32_e32 v44, v4
	v_mov_b32_e32 v45, v4
	v_mov_b32_e32 v46, v4
	v_mov_b32_e32 v47, v4
	v_mov_b32_e32 v48, v4
	v_mov_b32_e32 v49, v4
	v_mov_b32_e32 v50, v4
	v_mov_b32_e32 v51, v4
	v_mov_b32_e32 v60, v4
	v_mov_b32_e32 v61, v4
	v_mov_b32_e32 v62, v4
	v_mov_b32_e32 v63, v4
	v_mov_b32_e32 v64, v4
	v_mov_b32_e32 v65, v4
	v_mov_b32_e32 v66, v4
	v_mov_b32_e32 v67, v4
	v_mov_b32_e32 v68, v4
	v_mov_b32_e32 v69, v4
	v_mov_b32_e32 v70, v4
	v_mov_b32_e32 v71, v4
	v_mov_b32_e32 v72, v4
	v_mov_b32_e32 v73, v4
	v_mov_b32_e32 v74, v4
	v_mov_b32_e32 v75, v4
	v_mov_b32_e32 v84, v4
	v_mov_b32_e32 v85, v4
	v_mov_b32_e32 v86, v4
	v_mov_b32_e32 v87, v4
	v_mov_b32_e32 v88, v4
	v_mov_b32_e32 v89, v4
	v_mov_b32_e32 v90, v4
	v_mov_b32_e32 v91, v4
	v_mov_b32_e32 v100, v4
	v_mov_b32_e32 v101, v4
	v_mov_b32_e32 v102, v4
	v_mov_b32_e32 v103, v4
	v_mov_b32_e32 v104, v4
	v_mov_b32_e32 v105, v4
	v_mov_b32_e32 v106, v4
	v_mov_b32_e32 v107, v4
	v_mov_b32_e32 v116, v4
	v_mov_b32_e32 v117, v4
	v_mov_b32_e32 v118, v4
	v_mov_b32_e32 v119, v4
	v_mov_b32_e32 v120, v4
	v_mov_b32_e32 v121, v4
	v_mov_b32_e32 v122, v4
	v_mov_b32_e32 v123, v4
	v_mov_b32_e32 v76, v4
	v_mov_b32_e32 v77, v4
	v_mov_b32_e32 v78, v4
	v_mov_b32_e32 v79, v4
	v_mov_b32_e32 v80, v4
	v_mov_b32_e32 v81, v4
	v_mov_b32_e32 v82, v4
	v_mov_b32_e32 v83, v4
	v_mov_b32_e32 v92, v4
	v_mov_b32_e32 v93, v4
	v_mov_b32_e32 v94, v4
	v_mov_b32_e32 v95, v4
	v_mov_b32_e32 v96, v4
	v_mov_b32_e32 v97, v4
	v_mov_b32_e32 v98, v4
	v_mov_b32_e32 v99, v4
	v_mov_b32_e32 v108, v4
	v_mov_b32_e32 v109, v4
	v_mov_b32_e32 v110, v4
	v_mov_b32_e32 v111, v4
	v_mov_b32_e32 v112, v4
	v_mov_b32_e32 v113, v4
	v_mov_b32_e32 v114, v4
	v_mov_b32_e32 v115, v4
	v_mov_b32_e32 v124, v4
	v_mov_b32_e32 v125, v4
	v_mov_b32_e32 v126, v4
	v_mov_b32_e32 v127, v4
	v_mov_b32_e32 v128, v4
	v_mov_b32_e32 v129, v4
	v_mov_b32_e32 v130, v4
	v_mov_b32_e32 v131, v4
	v_readfirstlane_b32 s98, v151
	s_nop 3
	s_lshr_b32 s98, s98, 8
	s_cmp_lg_u32 s98, 0
	s_cbranch_scc0 .Lprio_skip_98
	s_setprio 1
.Lprio_skip_98:
.LBB0_98:
	s_add_u32 s22, s20, 0xfff80080
	s_addc_u32 s23, s21, -1
	s_add_i32 s48, 0, 0x10000
	v_add_u32_e32 v146, s48, v163
	ds_read_b128 v[142:145], v146
	ds_read_b128 v[174:177], v146 offset:1024
	ds_read_b128 v[178:181], v146 offset:2048
	ds_read_b128 v[182:185], v146 offset:3072
	s_cmp_eq_u32 s47, 28
	s_cselect_b32 s25, s13, s23
	s_cselect_b32 s24, s42, s22
	s_cselect_b32 s23, s9, s46
	s_cselect_b32 s22, s43, s44
	v_lshl_add_u64 v[146:147], s[20:21], 0, v[138:139]
	s_add_i32 m0, s19, 0xc000
	ds_read_b128 v[186:189], v173
	ds_read_b128 v[190:193], v173 offset:1024
	ds_read_b128 v[194:197], v173 offset:2048
	ds_read_b128 v[198:201], v173 offset:3072
	ds_read_b128 v[214:217], v173 offset:4096
	ds_read_b128 v[218:221], v173 offset:5120
	ds_read_b128 v[222:225], v173 offset:6144
	ds_read_b128 v[226:229], v173 offset:7168
	global_load_lds_dwordx4 v[146:147], off
	v_lshl_add_u64 v[146:147], s[20:21], 0, v[140:141]
	s_add_i32 m0, s19, 0xe000
	s_nop 0
	global_load_lds_dwordx4 v[146:147], off
	s_waitcnt lgkmcnt(8)
	s_barrier
	s_waitcnt lgkmcnt(0)
	s_waitcnt lgkmcnt(0)
	v_mfma_f32_16x16x32_bf16 v[128:131], v[142:145], v[186:189], v[128:131]
	v_mfma_f32_16x16x32_bf16 v[124:127], v[178:181], v[186:189], v[124:127]
	v_mfma_f32_16x16x32_bf16 v[112:115], v[142:145], v[194:197], v[112:115]
	v_mfma_f32_16x16x32_bf16 v[108:111], v[178:181], v[194:197], v[108:111]
	v_mfma_f32_16x16x32_bf16 v[96:99], v[142:145], v[214:217], v[96:99]
	v_mfma_f32_16x16x32_bf16 v[92:95], v[178:181], v[214:217], v[92:95]
	v_mfma_f32_16x16x32_bf16 v[80:83], v[142:145], v[222:225], v[80:83]
	v_mfma_f32_16x16x32_bf16 v[76:79], v[178:181], v[222:225], v[76:79]
	v_mfma_f32_16x16x32_bf16 v[128:131], v[174:177], v[190:193], v[128:131]
	v_mfma_f32_16x16x32_bf16 v[124:127], v[182:185], v[190:193], v[124:127]
	v_mfma_f32_16x16x32_bf16 v[112:115], v[174:177], v[198:201], v[112:115]
	v_mfma_f32_16x16x32_bf16 v[108:111], v[182:185], v[198:201], v[108:111]
	v_mfma_f32_16x16x32_bf16 v[96:99], v[174:177], v[218:221], v[96:99]
	v_mfma_f32_16x16x32_bf16 v[92:95], v[182:185], v[218:221], v[92:95]
	v_mfma_f32_16x16x32_bf16 v[80:83], v[174:177], v[226:229], v[80:83]
	v_mfma_f32_16x16x32_bf16 v[76:79], v[182:185], v[226:229], v[76:79]
	s_barrier
; #define PG8_STAGE(bufoff, gbase, voff) do { _Pragma("unroll") for (int _i = 0; _i < 2; ++_i) \
;         __builtin_amdgcn_global_load_lds((const unsigned*)((const char*)(gbase) + (voff)[_i]), (LAS unsigned*)(lds + (bufoff) + ldsw + _i * 8192), 16, 0, 0); } while (0)
; #define PG8_LDA(dst, b, h) do { _Pragma("unroll") for (int m = 0; m < 4; ++m) _Pragma("unroll") for (int k = 0; k < 2; ++k) dst[m][k] = *(const LAS bf16x8*)(lds + PG8_SA(b, h) + aoff + m * 2048 + k * 1024); } while (0)
; #define PG8_LDB(dst, b, h) do { _Pragma("unroll") for (int n = 0; n < 2; ++n) _Pragma("unroll") for (int k = 0; k < 2; ++k) dst[n][k] = *(const LAS bf16x8*)(lds + PG8_SB(b, h) + boff + n * 2048 + k * 1024); } while (0)
; #define PG8_MMA(ai, bj, At, Bt) do { __builtin_amdgcn_s_setprio(1); _Pragma("unroll") for (int m = 0; m < 4; ++m) _Pragma("unroll") for (int n = 0; n < 2; ++n) _Pragma("unroll") for (int k = 0; k < 2; ++k) \
;         acc[ai][bj][m][n] = __builtin_amdgcn_mfma_f32_16x16x32_bf16(Bt[n][k], At[m][k], acc[ai][bj][m][n], 0, 0, 0); __builtin_amdgcn_s_setprio(0); } while (0)
; #define PG8_WAIT_V(n) asm volatile("s_waitcnt vmcnt(" #n ")" ::: "memory")
; #define PG8_WAIT_L(n) asm volatile("s_waitcnt lgkmcnt(" #n ")" ::: "memory")
; #define PG8_BAR __builtin_amdgcn_s_barrier()
; #define PG8_SCHED __builtin_amdgcn_sched_barrier(0)
; template <class Epi>
; __device__ __forceinline__ void gemm_phase(LAS unsigned char* lds, const Gemm g, const StaticOrder& S, const Epi& E) {
;     ...
;             PG8_LDB(B1, 0, 1); PG8_STAGE(PG8_SB(0, 0), b2, voffB);
;             PG8_BAR; PG8_WAIT_L(0); PG8_MMA(0, 1, At, B1); PG8_BAR;
;             PG8_LDA(At, 0, 1); PG8_STAGE(PG8_SA(0, 0), a2, voffA);
;             PG8_BAR; PG8_WAIT_L(0); PG8_MMA(1, 0, At, B0); PG8_BAR; PG8_SCHED;
;             PG8_STAGE(PG8_SB(0, 1), b2 + hstep, voffB);
;             PG8_WAIT_V(6); PG8_BAR; PG8_MMA(1, 1, At, B1); PG8_BAR;
;             PG8_LDB(B0, 1, 0); PG8_SCHED; PG8_LDA(At, 1, 0); PG8_STAGE(PG8_SA(0, 1), a2 + hstep, voffA);
;             PG8_WAIT_L(8); PG8_BAR; PG8_WAIT_L(0); PG8_MMA(0, 0, At, B0); PG8_BAR; PG8_SCHED;
	s_add_i32 s52, 0, 0x14000
	v_add_u32_e32 v146, s52, v163
	s_add_i32 s48, s48, s31
	ds_read_b128 v[230:233], v146
	ds_read_b128 v[234:237], v146 offset:1024
	ds_read_b128 v[238:241], v146 offset:2048
	ds_read_b128 v[242:245], v146 offset:3072
	v_lshl_add_u64 v[146:147], s[22:23], 0, v[148:149]
	s_mov_b32 m0, s48
	v_lshl_add_u64 v[170:171], s[22:23], 0, v[136:137]
	global_load_lds_dwordx4 v[146:147], off
	s_add_i32 m0, s48, 0x2000
	s_nop 0
	global_load_lds_dwordx4 v[170:171], off
	s_barrier
	s_waitcnt lgkmcnt(0)
	s_waitcnt lgkmcnt(0)
	v_mfma_f32_16x16x32_bf16 v[120:123], v[230:233], v[186:189], v[120:123]
	v_mfma_f32_16x16x32_bf16 v[116:119], v[238:241], v[186:189], v[116:119]
	v_mfma_f32_16x16x32_bf16 v[104:107], v[230:233], v[194:197], v[104:107]
	v_mfma_f32_16x16x32_bf16 v[100:103], v[238:241], v[194:197], v[100:103]
	v_mfma_f32_16x16x32_bf16 v[88:91], v[230:233], v[214:217], v[88:91]
	v_mfma_f32_16x16x32_bf16 v[84:87], v[238:241], v[214:217], v[84:87]
	v_mfma_f32_16x16x32_bf16 v[72:75], v[230:233], v[222:225], v[72:75]
	v_mfma_f32_16x16x32_bf16 v[68:71], v[238:241], v[222:225], v[68:71]
	v_mfma_f32_16x16x32_bf16 v[120:123], v[234:237], v[190:193], v[120:123]
	v_mfma_f32_16x16x32_bf16 v[116:119], v[242:245], v[190:193], v[116:119]
	v_mfma_f32_16x16x32_bf16 v[104:107], v[234:237], v[198:201], v[104:107]
	v_mfma_f32_16x16x32_bf16 v[100:103], v[242:245], v[198:201], v[100:103]
	v_mfma_f32_16x16x32_bf16 v[88:91], v[234:237], v[218:221], v[88:91]
	v_mfma_f32_16x16x32_bf16 v[84:87], v[242:245], v[218:221], v[84:87]
	v_mfma_f32_16x16x32_bf16 v[72:75], v[234:237], v[226:229], v[72:75]
	v_mfma_f32_16x16x32_bf16 v[68:71], v[242:245], v[226:229], v[68:71]
	s_mov_b32 m0, s19
	v_lshl_add_u64 v[246:247], s[24:25], 0, v[132:133]
	s_barrier
	ds_read_b128 v[186:189], v173 offset:16384
	ds_read_b128 v[190:193], v173 offset:17408
	ds_read_b128 v[194:197], v173 offset:18432
	ds_read_b128 v[198:201], v173 offset:19456
	ds_read_b128 v[214:217], v173 offset:20480
	ds_read_b128 v[218:221], v173 offset:21504
	ds_read_b128 v[222:225], v173 offset:22528
	ds_read_b128 v[226:229], v173 offset:23552
	global_load_lds_dwordx4 v[246:247], off
	v_lshl_add_u64 v[248:249], s[24:25], 0, v[134:135]
	s_mov_b32 m0, s33
	s_nop 0
	global_load_lds_dwordx4 v[248:249], off
	s_barrier
	s_waitcnt lgkmcnt(0)
	s_waitcnt lgkmcnt(0)
	v_mfma_f32_16x16x32_bf16 v[64:67], v[142:145], v[186:189], v[64:67]
	v_mfma_f32_16x16x32_bf16 v[60:63], v[178:181], v[186:189], v[60:63]
	v_mfma_f32_16x16x32_bf16 v[48:51], v[142:145], v[194:197], v[48:51]
	v_mfma_f32_16x16x32_bf16 v[44:47], v[178:181], v[194:197], v[44:47]
	v_mfma_f32_16x16x32_bf16 v[32:35], v[142:145], v[214:217], v[32:35]
	v_mfma_f32_16x16x32_bf16 v[28:31], v[178:181], v[214:217], v[28:31]
	v_mfma_f32_16x16x32_bf16 v[16:19], v[142:145], v[222:225], v[16:19]
	v_mfma_f32_16x16x32_bf16 v[12:15], v[178:181], v[222:225], v[12:15]
	v_mfma_f32_16x16x32_bf16 v[64:67], v[174:177], v[190:193], v[64:67]
	v_mfma_f32_16x16x32_bf16 v[60:63], v[182:185], v[190:193], v[60:63]
	v_mfma_f32_16x16x32_bf16 v[48:51], v[174:177], v[198:201], v[48:51]
	v_mfma_f32_16x16x32_bf16 v[44:47], v[182:185], v[198:201], v[44:47]
	v_mfma_f32_16x16x32_bf16 v[32:35], v[174:177], v[218:221], v[32:35]
	v_mfma_f32_16x16x32_bf16 v[28:31], v[182:185], v[218:221], v[28:31]
	v_mfma_f32_16x16x32_bf16 v[16:19], v[174:177], v[226:229], v[16:19]
	v_mfma_f32_16x16x32_bf16 v[12:15], v[182:185], v[226:229], v[12:15]
	s_barrier
	s_add_u32 s72, s22, 0x80000
	s_addc_u32 s73, s23, 0
	s_add_i32 s48, s52, s31
	v_lshl_add_u64 v[142:143], s[72:73], 0, v[148:149]
	s_mov_b32 m0, s48
	s_nop 0
	global_load_lds_dwordx4 v[142:143], off
	v_lshl_add_u64 v[142:143], s[72:73], 0, v[136:137]
	s_add_i32 m0, s48, 0x2000
	s_nop 0
	global_load_lds_dwordx4 v[142:143], off
	s_waitcnt vmcnt(6)
	s_barrier
	v_mfma_f32_16x16x32_bf16 v[56:59], v[230:233], v[186:189], v[56:59]
	v_mfma_f32_16x16x32_bf16 v[52:55], v[238:241], v[186:189], v[52:55]
	v_mfma_f32_16x16x32_bf16 v[40:43], v[230:233], v[194:197], v[40:43]
	v_mfma_f32_16x16x32_bf16 v[36:39], v[238:241], v[194:197], v[36:39]
	v_mfma_f32_16x16x32_bf16 v[24:27], v[230:233], v[214:217], v[24:27]
	v_mfma_f32_16x16x32_bf16 v[20:23], v[238:241], v[214:217], v[20:23]
	v_mfma_f32_16x16x32_bf16 v[8:11], v[230:233], v[222:225], v[8:11]
	v_mfma_f32_16x16x32_bf16 v[4:7], v[238:241], v[222:225], v[4:7]
	v_mfma_f32_16x16x32_bf16 v[56:59], v[234:237], v[190:193], v[56:59]
	v_mfma_f32_16x16x32_bf16 v[52:55], v[242:245], v[190:193], v[52:55]
	v_mfma_f32_16x16x32_bf16 v[40:43], v[234:237], v[198:201], v[40:43]
	v_mfma_f32_16x16x32_bf16 v[36:39], v[242:245], v[198:201], v[36:39]
	v_mfma_f32_16x16x32_bf16 v[24:27], v[234:237], v[218:221], v[24:27]
	v_mfma_f32_16x16x32_bf16 v[20:23], v[242:245], v[218:221], v[20:23]
	v_mfma_f32_16x16x32_bf16 v[8:11], v[234:237], v[226:229], v[8:11]
	v_mfma_f32_16x16x32_bf16 v[4:7], v[242:245], v[226:229], v[4:7]
	s_add_i32 s48, 0, 0x18000
	v_add_u32_e32 v182, s48, v163
	s_barrier
	ds_read_b128 v[142:145], v182
	ds_read_b128 v[174:177], v182 offset:1024
	ds_read_b128 v[178:181], v182 offset:2048
	ds_read_b128 v[182:185], v182 offset:3072
	s_add_u32 s24, s24, 0x80000
	s_addc_u32 s25, s25, 0
	s_mov_b32 m0, s36
	v_lshl_add_u64 v[230:231], s[24:25], 0, v[132:133]
	ds_read_b128 v[186:189], v173 offset:32768
	ds_read_b128 v[190:193], v173 offset:33792
	ds_read_b128 v[194:197], v173 offset:34816
	ds_read_b128 v[198:201], v173 offset:35840
	ds_read_b128 v[214:217], v173 offset:36864
	ds_read_b128 v[218:221], v173 offset:37888
	ds_read_b128 v[222:225], v173 offset:38912
	ds_read_b128 v[226:229], v173 offset:39936
	global_load_lds_dwordx4 v[230:231], off
	v_lshl_add_u64 v[230:231], s[24:25], 0, v[134:135]
	s_mov_b32 m0, s37
	s_nop 0
	global_load_lds_dwordx4 v[230:231], off
	s_waitcnt lgkmcnt(8)
	s_barrier
; #define PG8_STAGE(bufoff, gbase, voff) do { _Pragma("unroll") for (int _i = 0; _i < 2; ++_i) \
;         __builtin_amdgcn_global_load_lds((const unsigned*)((const char*)(gbase) + (voff)[_i]), (LAS unsigned*)(lds + (bufoff) + ldsw + _i * 8192), 16, 0, 0); } while (0)
; #define PG8_LDA(dst, b, h) do { _Pragma("unroll") for (int m = 0; m < 4; ++m) _Pragma("unroll") for (int k = 0; k < 2; ++k) dst[m][k] = *(const LAS bf16x8*)(lds + PG8_SA(b, h) + aoff + m * 2048 + k * 1024); } while (0)
; #define PG8_LDB(dst, b, h) do { _Pragma("unroll") for (int n = 0; n < 2; ++n) _Pragma("unroll") for (int k = 0; k < 2; ++k) dst[n][k] = *(const LAS bf16x8*)(lds + PG8_SB(b, h) + boff + n * 2048 + k * 1024); } while (0)
; #define PG8_MMA(ai, bj, At, Bt) do { __builtin_amdgcn_s_setprio(1); _Pragma("unroll") for (int m = 0; m < 4; ++m) _Pragma("unroll") for (int n = 0; n < 2; ++n) _Pragma("unroll") for (int k = 0; k < 2; ++k) \
;         acc[ai][bj][m][n] = __builtin_amdgcn_mfma_f32_16x16x32_bf16(Bt[n][k], At[m][k], acc[ai][bj][m][n], 0, 0, 0); __builtin_amdgcn_s_setprio(0); } while (0)
; #define PG8_WAIT_V(n) asm volatile("s_waitcnt vmcnt(" #n ")" ::: "memory")
; #define PG8_WAIT_L(n) asm volatile("s_waitcnt lgkmcnt(" #n ")" ::: "memory")
; #define PG8_BAR __builtin_amdgcn_s_barrier()
; #define PG8_SCHED __builtin_amdgcn_sched_barrier(0)
; template <class Epi>
; __device__ __forceinline__ void gemm_phase(LAS unsigned char* lds, const Gemm g, const StaticOrder& S, const Epi& E) {
;     ...
;             PG8_WAIT_L(8); PG8_BAR; PG8_WAIT_L(0); PG8_MMA(0, 0, At, B0); PG8_BAR; PG8_SCHED;
;             PG8_LDB(B1, 1, 1); PG8_STAGE(PG8_SB(1, 0), b3, voffB);
;             PG8_BAR; PG8_WAIT_L(0); PG8_MMA(0, 1, At, B1); PG8_BAR;
;             PG8_LDA(At, 1, 1); PG8_STAGE(PG8_SA(1, 0), a3, voffA);
;             PG8_BAR; PG8_WAIT_L(0); PG8_MMA(1, 0, At, B0); PG8_BAR; PG8_SCHED;
;             PG8_STAGE(PG8_SB(1, 1), b3 + hstep, voffB);
;             PG8_WAIT_V(6); PG8_BAR; PG8_MMA(1, 1, At, B1); PG8_BAR;
	s_waitcnt lgkmcnt(0)
	s_waitcnt lgkmcnt(0)
	v_mfma_f32_16x16x32_bf16 v[128:131], v[142:145], v[186:189], v[128:131]
	v_mfma_f32_16x16x32_bf16 v[124:127], v[178:181], v[186:189], v[124:127]
	v_mfma_f32_16x16x32_bf16 v[112:115], v[142:145], v[194:197], v[112:115]
	v_mfma_f32_16x16x32_bf16 v[108:111], v[178:181], v[194:197], v[108:111]
	v_mfma_f32_16x16x32_bf16 v[96:99], v[142:145], v[214:217], v[96:99]
	v_mfma_f32_16x16x32_bf16 v[92:95], v[178:181], v[214:217], v[92:95]
	v_mfma_f32_16x16x32_bf16 v[80:83], v[142:145], v[222:225], v[80:83]
	v_mfma_f32_16x16x32_bf16 v[76:79], v[178:181], v[222:225], v[76:79]
	v_mfma_f32_16x16x32_bf16 v[128:131], v[174:177], v[190:193], v[128:131]
	v_mfma_f32_16x16x32_bf16 v[124:127], v[182:185], v[190:193], v[124:127]
	v_mfma_f32_16x16x32_bf16 v[112:115], v[174:177], v[198:201], v[112:115]
	v_mfma_f32_16x16x32_bf16 v[108:111], v[182:185], v[198:201], v[108:111]
	v_mfma_f32_16x16x32_bf16 v[96:99], v[174:177], v[218:221], v[96:99]
	v_mfma_f32_16x16x32_bf16 v[92:95], v[182:185], v[218:221], v[92:95]
	v_mfma_f32_16x16x32_bf16 v[80:83], v[174:177], v[226:229], v[80:83]
	v_mfma_f32_16x16x32_bf16 v[76:79], v[182:185], v[226:229], v[76:79]
	s_barrier
	s_add_i32 s24, 0, 0x1c000
	s_add_i32 s25, s48, s31
	v_add_u32_e32 v242, s24, v163
	v_lshl_add_u64 v[146:147], v[146:147], 0, s[34:35]
	s_mov_b32 m0, s25
	ds_read_b128 v[230:233], v242
	ds_read_b128 v[234:237], v242 offset:1024
	ds_read_b128 v[238:241], v242 offset:2048
	ds_read_b128 v[242:245], v242 offset:3072
	global_load_lds_dwordx4 v[146:147], off
	v_lshl_add_u64 v[146:147], v[170:171], 0, s[34:35]
	s_add_i32 m0, s25, 0x2000
	s_nop 0
	global_load_lds_dwordx4 v[146:147], off
	s_barrier
	s_waitcnt lgkmcnt(0)
	s_waitcnt lgkmcnt(0)
	v_mfma_f32_16x16x32_bf16 v[120:123], v[230:233], v[186:189], v[120:123]
	v_mfma_f32_16x16x32_bf16 v[116:119], v[238:241], v[186:189], v[116:119]
	v_mfma_f32_16x16x32_bf16 v[104:107], v[230:233], v[194:197], v[104:107]
	v_mfma_f32_16x16x32_bf16 v[100:103], v[238:241], v[194:197], v[100:103]
	v_mfma_f32_16x16x32_bf16 v[88:91], v[230:233], v[214:217], v[88:91]
	v_mfma_f32_16x16x32_bf16 v[84:87], v[238:241], v[214:217], v[84:87]
	v_mfma_f32_16x16x32_bf16 v[72:75], v[230:233], v[222:225], v[72:75]
	v_mfma_f32_16x16x32_bf16 v[68:71], v[238:241], v[222:225], v[68:71]
	v_mfma_f32_16x16x32_bf16 v[120:123], v[234:237], v[190:193], v[120:123]
	v_mfma_f32_16x16x32_bf16 v[116:119], v[242:245], v[190:193], v[116:119]
	v_mfma_f32_16x16x32_bf16 v[104:107], v[234:237], v[198:201], v[104:107]
	v_mfma_f32_16x16x32_bf16 v[100:103], v[242:245], v[198:201], v[100:103]
	v_mfma_f32_16x16x32_bf16 v[88:91], v[234:237], v[218:221], v[88:91]
	v_mfma_f32_16x16x32_bf16 v[84:87], v[242:245], v[218:221], v[84:87]
	v_mfma_f32_16x16x32_bf16 v[72:75], v[234:237], v[226:229], v[72:75]
	v_mfma_f32_16x16x32_bf16 v[68:71], v[242:245], v[226:229], v[68:71]
	s_mov_b32 m0, s38
	v_lshl_add_u64 v[146:147], v[246:247], 0, s[34:35]
	s_barrier
	ds_read_b128 v[186:189], v173 offset:49152
	ds_read_b128 v[190:193], v173 offset:50176
	ds_read_b128 v[194:197], v173 offset:51200
	ds_read_b128 v[198:201], v173 offset:52224
	ds_read_b128 v[214:217], v173 offset:53248
	ds_read_b128 v[218:221], v173 offset:54272
	ds_read_b128 v[222:225], v173 offset:55296
	ds_read_b128 v[226:229], v173 offset:56320
	global_load_lds_dwordx4 v[146:147], off
	v_lshl_add_u64 v[146:147], v[248:249], 0, s[34:35]
	s_mov_b32 m0, s39
	s_nop 0
	global_load_lds_dwordx4 v[146:147], off
	s_barrier
	s_waitcnt lgkmcnt(0)
	s_waitcnt lgkmcnt(0)
	v_mfma_f32_16x16x32_bf16 v[64:67], v[142:145], v[186:189], v[64:67]
	v_mfma_f32_16x16x32_bf16 v[60:63], v[178:181], v[186:189], v[60:63]
	v_mfma_f32_16x16x32_bf16 v[48:51], v[142:145], v[194:197], v[48:51]
	v_mfma_f32_16x16x32_bf16 v[44:47], v[178:181], v[194:197], v[44:47]
	v_mfma_f32_16x16x32_bf16 v[32:35], v[142:145], v[214:217], v[32:35]
	v_mfma_f32_16x16x32_bf16 v[28:31], v[178:181], v[214:217], v[28:31]
	v_mfma_f32_16x16x32_bf16 v[16:19], v[142:145], v[222:225], v[16:19]
	v_mfma_f32_16x16x32_bf16 v[12:15], v[178:181], v[222:225], v[12:15]
	v_mfma_f32_16x16x32_bf16 v[64:67], v[174:177], v[190:193], v[64:67]
	v_mfma_f32_16x16x32_bf16 v[60:63], v[182:185], v[190:193], v[60:63]
	v_mfma_f32_16x16x32_bf16 v[48:51], v[174:177], v[198:201], v[48:51]
	v_mfma_f32_16x16x32_bf16 v[44:47], v[182:185], v[198:201], v[44:47]
	v_mfma_f32_16x16x32_bf16 v[32:35], v[174:177], v[218:221], v[32:35]
	v_mfma_f32_16x16x32_bf16 v[28:31], v[182:185], v[218:221], v[28:31]
	v_mfma_f32_16x16x32_bf16 v[16:19], v[174:177], v[226:229], v[16:19]
	v_mfma_f32_16x16x32_bf16 v[12:15], v[182:185], v[226:229], v[12:15]
	s_barrier
	s_add_u32 s22, s22, 0x80080
	s_addc_u32 s23, s23, 0
	s_add_i32 s24, s24, s31
	v_lshl_add_u64 v[142:143], s[22:23], 0, v[148:149]
	s_mov_b32 m0, s24
	s_nop 0
	global_load_lds_dwordx4 v[142:143], off
	v_lshl_add_u64 v[142:143], s[22:23], 0, v[136:137]
	s_add_i32 m0, s24, 0x2000
	s_nop 0
	global_load_lds_dwordx4 v[142:143], off
	s_waitcnt vmcnt(6)
	s_barrier
	v_mfma_f32_16x16x32_bf16 v[56:59], v[230:233], v[186:189], v[56:59]
	v_mfma_f32_16x16x32_bf16 v[52:55], v[238:241], v[186:189], v[52:55]
	v_mfma_f32_16x16x32_bf16 v[40:43], v[230:233], v[194:197], v[40:43]
	v_mfma_f32_16x16x32_bf16 v[36:39], v[238:241], v[194:197], v[36:39]
	v_mfma_f32_16x16x32_bf16 v[24:27], v[230:233], v[214:217], v[24:27]
	v_mfma_f32_16x16x32_bf16 v[20:23], v[238:241], v[214:217], v[20:23]
	v_mfma_f32_16x16x32_bf16 v[8:11], v[230:233], v[222:225], v[8:11]
	v_mfma_f32_16x16x32_bf16 v[4:7], v[238:241], v[222:225], v[4:7]
	v_mfma_f32_16x16x32_bf16 v[56:59], v[234:237], v[190:193], v[56:59]
	v_mfma_f32_16x16x32_bf16 v[52:55], v[242:245], v[190:193], v[52:55]
	v_mfma_f32_16x16x32_bf16 v[40:43], v[234:237], v[198:201], v[40:43]
	v_mfma_f32_16x16x32_bf16 v[36:39], v[242:245], v[198:201], v[36:39]
	v_mfma_f32_16x16x32_bf16 v[24:27], v[234:237], v[218:221], v[24:27]
	v_mfma_f32_16x16x32_bf16 v[20:23], v[242:245], v[218:221], v[20:23]
	v_mfma_f32_16x16x32_bf16 v[8:11], v[234:237], v[226:229], v[8:11]
	v_mfma_f32_16x16x32_bf16 v[4:7], v[242:245], v[226:229], v[4:7]
	s_add_i32 s47, s47, 2
	s_add_u32 s20, s20, 0x100
	s_addc_u32 s21, s21, 0
	s_add_u32 s44, s44, 0x100
	s_addc_u32 s46, s46, 0
	s_cmp_gt_u32 s47, 29
	s_barrier
; __device__ __forceinline__ unsigned pack2(float lo, float hi) { unsigned r; asm("v_cvt_pk_bf16_f32 %0, %1, %2" : "=v"(r) : "v"(lo), "v"(hi)); return r; }
;     __device__ __forceinline__ void operator()(const AccT& acc, const pg8::Unit& u, int wr, int wc, int fr, int fq) const {
;     ...
;         for (int ai = 0; ai < 2; ++ai)
; #pragma unroll
;             for (int m = 0; m < 4; ++m) {
;                 const int row = row0 + ai * 128 + m * 16;
;                 const float r2 = rsqrtf(SS2[row] * (1.f / 2048.f) + EPS);
;                 bf16_t* rowp = UP + (size_t)row * N3 + col0;
; #pragma unroll
;                 for (int bj = 0; bj < 2; ++bj) {
;                     const f32x4 v0 = acc[ai][bj][m][0] * r2, v1 = acc[ai][bj][m][1] * r2;
;                     u32x4 o; o[0] = pack2(v0[0], v0[1]); o[1] = pack2(v0[2], v0[3]); o[2] = pack2(v1[0], v1[1]); o[3] = pack2(v1[2], v1[3]);
;                     *(u32x4*)(rowp + bj * 128) = o;
;                 }
;             }
	s_cbranch_scc0 .LBB0_98
	s_setprio 0
	s_mov_b32 s13, 0x800000
	v_lshl_add_u32 v142, s18, 8, v153
	v_ashrrev_i32_e32 v143, 31, v142
	v_lshl_add_u64 v[144:145], v[142:143], 2, s[6:7]
	global_load_dword v246, v[144:145], off
	global_load_dword v247, v[144:145], off offset:64
	global_load_dword v248, v[144:145], off offset:128
	global_load_dword v249, v[144:145], off offset:192
	global_load_dword v250, v[144:145], off offset:512
	global_load_dword v251, v[144:145], off offset:576
	global_load_dword v252, v[144:145], off offset:640
	global_load_dword v253, v[144:145], off offset:704
	v_lshl_or_b32 v170, s41, 8, v172
	v_ashrrev_i32_e32 v171, 31, v170
	s_movk_i32 s9, 0x5800
	v_lshlrev_b64 v[170:171], 1, v[170:171]
	s_mov_b32 s18, s12
	s_mov_b32 s41, s8
	s_mov_b64 s[22:23], s[16:17]
	s_waitcnt vmcnt(0)
	v_mov_b32_e32 v143, v246
	v_fmamk_f32 v143, v143, 0x3a000000, v202
	v_cmp_gt_f32_e32 vcc, s13, v143
	v_mul_f32_e32 v146, 0x4b800000, v143
	s_nop 0
	v_cndmask_b32_e32 v143, v143, v146, vcc
	v_rsq_f32_e32 v143, v143
	s_nop 0
	v_mul_f32_e32 v146, 0x45800000, v143
	v_cndmask_b32_e32 v174, v143, v146, vcc
	v_mov_b64_e32 v[146:147], s[4:5]
	v_mad_i64_i32 v[176:177], s[20:21], v142, s9, v[146:147]
	v_lshl_add_u64 v[176:177], v[176:177], 0, v[170:171]
	v_pk_mul_f32 v[130:131], v[130:131], v[174:175] op_sel_hi:[1,0]
	v_pk_mul_f32 v[128:129], v[128:129], v[174:175] op_sel_hi:[1,0]
	v_pk_mul_f32 v[178:179], v[126:127], v[174:175] op_sel_hi:[1,0]
	v_pk_mul_f32 v[126:127], v[124:125], v[174:175] op_sel_hi:[1,0]
	v_cvt_pk_bf16_f32 v124, v128, v129
	v_cvt_pk_bf16_f32 v125, v130, v131
	v_pk_mul_f32 v[120:121], v[120:121], v[174:175] op_sel_hi:[1,0]
	v_cvt_pk_bf16_f32 v126, v126, v127
	v_cvt_pk_bf16_f32 v127, v178, v179
	global_store_dwordx4 v[176:177], v[124:127], off
	v_pk_mul_f32 v[122:123], v[122:123], v[174:175] op_sel_hi:[1,0]
	s_nop 0
	v_pk_mul_f32 v[124:125], v[118:119], v[174:175] op_sel_hi:[1,0]
	v_pk_mul_f32 v[118:119], v[116:117], v[174:175] op_sel_hi:[1,0]
	v_cvt_pk_bf16_f32 v116, v120, v121
	v_cvt_pk_bf16_f32 v117, v122, v123
	s_nop 0
	v_cvt_pk_bf16_f32 v118, v118, v119
	v_cvt_pk_bf16_f32 v119, v124, v125
	global_store_dwordx4 v[176:177], v[116:119], off offset:256
	s_nop 1
	v_or_b32_e32 v116, 16, v142
	v_ashrrev_i32_e32 v117, 31, v116
	v_lshl_add_u64 v[118:119], v[116:117], 2, s[6:7]
	s_nop 1
	v_mov_b32_e32 v117, v247
	v_fmamk_f32 v117, v117, 0x3a000000, v202
	v_cmp_gt_f32_e32 vcc, s13, v117
	v_mul_f32_e32 v118, 0x4b800000, v117
	s_nop 0
	v_cndmask_b32_e32 v117, v117, v118, vcc
	v_rsq_f32_e32 v117, v117
	s_nop 0
	v_mul_f32_e32 v118, 0x45800000, v117
	v_cndmask_b32_e32 v118, v117, v118, vcc
	v_mad_i64_i32 v[116:117], s[20:21], v116, s9, v[146:147]
	v_lshl_add_u64 v[116:117], v[116:117], 0, v[170:171]
	v_pk_mul_f32 v[114:115], v[114:115], v[118:119] op_sel_hi:[1,0]
	v_pk_mul_f32 v[112:113], v[112:113], v[118:119] op_sel_hi:[1,0]
	v_pk_mul_f32 v[120:121], v[110:111], v[118:119] op_sel_hi:[1,0]
	v_pk_mul_f32 v[110:111], v[108:109], v[118:119] op_sel_hi:[1,0]
	v_cvt_pk_bf16_f32 v108, v112, v113
	v_cvt_pk_bf16_f32 v109, v114, v115
	v_pk_mul_f32 v[104:105], v[104:105], v[118:119] op_sel_hi:[1,0]
	v_cvt_pk_bf16_f32 v110, v110, v111
	v_cvt_pk_bf16_f32 v111, v120, v121
	global_store_dwordx4 v[116:117], v[108:111], off
	v_pk_mul_f32 v[106:107], v[106:107], v[118:119] op_sel_hi:[1,0]
	s_nop 0
	v_pk_mul_f32 v[108:109], v[102:103], v[118:119] op_sel_hi:[1,0]
	v_pk_mul_f32 v[102:103], v[100:101], v[118:119] op_sel_hi:[1,0]
	v_cvt_pk_bf16_f32 v100, v104, v105
	v_cvt_pk_bf16_f32 v101, v106, v107
	s_nop 0
	v_cvt_pk_bf16_f32 v102, v102, v103
	v_cvt_pk_bf16_f32 v103, v108, v109
	global_store_dwordx4 v[116:117], v[100:103], off offset:256
	s_nop 1
	v_or_b32_e32 v100, 32, v142
	v_ashrrev_i32_e32 v101, 31, v100
	v_lshl_add_u64 v[102:103], v[100:101], 2, s[6:7]
	s_nop 1
	v_mov_b32_e32 v101, v248
	v_fmamk_f32 v101, v101, 0x3a000000, v202
	v_cmp_gt_f32_e32 vcc, s13, v101
	v_mul_f32_e32 v102, 0x4b800000, v101
	s_nop 0
	v_cndmask_b32_e32 v101, v101, v102, vcc
	v_rsq_f32_e32 v101, v101
	s_nop 0
	v_mul_f32_e32 v102, 0x45800000, v101
	v_cndmask_b32_e32 v102, v101, v102, vcc
	v_mad_i64_i32 v[100:101], s[20:21], v100, s9, v[146:147]
	v_lshl_add_u64 v[100:101], v[100:101], 0, v[170:171]
	v_pk_mul_f32 v[98:99], v[98:99], v[102:103] op_sel_hi:[1,0]
	v_pk_mul_f32 v[96:97], v[96:97], v[102:103] op_sel_hi:[1,0]
	v_pk_mul_f32 v[104:105], v[94:95], v[102:103] op_sel_hi:[1,0]
	v_pk_mul_f32 v[94:95], v[92:93], v[102:103] op_sel_hi:[1,0]
	v_cvt_pk_bf16_f32 v92, v96, v97
	v_cvt_pk_bf16_f32 v93, v98, v99
	v_pk_mul_f32 v[88:89], v[88:89], v[102:103] op_sel_hi:[1,0]
	v_cvt_pk_bf16_f32 v94, v94, v95
	v_cvt_pk_bf16_f32 v95, v104, v105
	global_store_dwordx4 v[100:101], v[92:95], off
	v_pk_mul_f32 v[90:91], v[90:91], v[102:103] op_sel_hi:[1,0]
	s_nop 0
	v_pk_mul_f32 v[92:93], v[86:87], v[102:103] op_sel_hi:[1,0]
	v_pk_mul_f32 v[86:87], v[84:85], v[102:103] op_sel_hi:[1,0]
	v_cvt_pk_bf16_f32 v84, v88, v89
	v_cvt_pk_bf16_f32 v85, v90, v91
	s_nop 0
	v_cvt_pk_bf16_f32 v86, v86, v87
	v_cvt_pk_bf16_f32 v87, v92, v93
	global_store_dwordx4 v[100:101], v[84:87], off offset:256
	s_nop 1
	v_or_b32_e32 v84, 48, v142
	v_ashrrev_i32_e32 v85, 31, v84
	v_lshl_add_u64 v[86:87], v[84:85], 2, s[6:7]
	s_nop 1
	v_mov_b32_e32 v85, v249
	v_fmamk_f32 v85, v85, 0x3a000000, v202
	v_cmp_gt_f32_e32 vcc, s13, v85
	v_mul_f32_e32 v86, 0x4b800000, v85
	s_nop 0
	v_cndmask_b32_e32 v85, v85, v86, vcc
	v_rsq_f32_e32 v85, v85
	s_nop 0
	v_mul_f32_e32 v86, 0x45800000, v85
	v_cndmask_b32_e32 v86, v85, v86, vcc
	v_mad_i64_i32 v[84:85], s[20:21], v84, s9, v[146:147]
	v_lshl_add_u64 v[84:85], v[84:85], 0, v[170:171]
; __device__ __forceinline__ unsigned pack2(float lo, float hi) { unsigned r; asm("v_cvt_pk_bf16_f32 %0, %1, %2" : "=v"(r) : "v"(lo), "v"(hi)); return r; }
; template <class Epi>
; __device__ __forceinline__ void gemm_phase(LAS unsigned char* lds, const Gemm g, const StaticOrder& S, const Epi& E) {
;     ...
;         if (!has_next) break;
;     __device__ __forceinline__ void operator()(const AccT& acc, const pg8::Unit& u, int wr, int wc, int fr, int fq) const {
;     ...
;             for (int m = 0; m < 4; ++m) {
;                 const int row = row0 + ai * 128 + m * 16;
;                 const float r2 = rsqrtf(SS2[row] * (1.f / 2048.f) + EPS);
;                 bf16_t* rowp = UP + (size_t)row * N3 + col0;
; #pragma unroll
;                 for (int bj = 0; bj < 2; ++bj) {
;                     const f32x4 v0 = acc[ai][bj][m][0] * r2, v1 = acc[ai][bj][m][1] * r2;
;                     u32x4 o; o[0] = pack2(v0[0], v0[1]); o[1] = pack2(v0[2], v0[3]); o[2] = pack2(v1[0], v1[1]); o[3] = pack2(v1[2], v1[3]);
;                     *(u32x4*)(rowp + bj * 128) = o;
;                 }
;             }
	v_pk_mul_f32 v[82:83], v[82:83], v[86:87] op_sel_hi:[1,0]
	v_pk_mul_f32 v[80:81], v[80:81], v[86:87] op_sel_hi:[1,0]
	v_pk_mul_f32 v[88:89], v[78:79], v[86:87] op_sel_hi:[1,0]
	v_pk_mul_f32 v[78:79], v[76:77], v[86:87] op_sel_hi:[1,0]
	v_cvt_pk_bf16_f32 v76, v80, v81
	v_cvt_pk_bf16_f32 v77, v82, v83
	v_pk_mul_f32 v[74:75], v[74:75], v[86:87] op_sel_hi:[1,0]
	v_cvt_pk_bf16_f32 v78, v78, v79
	v_cvt_pk_bf16_f32 v79, v88, v89
	global_store_dwordx4 v[84:85], v[76:79], off
	v_pk_mul_f32 v[72:73], v[72:73], v[86:87] op_sel_hi:[1,0]
	s_nop 0
	v_pk_mul_f32 v[76:77], v[70:71], v[86:87] op_sel_hi:[1,0]
	v_pk_mul_f32 v[70:71], v[68:69], v[86:87] op_sel_hi:[1,0]
	v_cvt_pk_bf16_f32 v68, v72, v73
	v_cvt_pk_bf16_f32 v69, v74, v75
	s_nop 0
	v_cvt_pk_bf16_f32 v70, v70, v71
	v_cvt_pk_bf16_f32 v71, v76, v77
	global_store_dwordx4 v[84:85], v[68:71], off offset:256
	s_nop 1
	v_mov_b32_e32 v68, v250
	s_nop 0
	v_add_u32_e32 v69, 0x80, v142
	v_fmamk_f32 v68, v68, 0x3a000000, v202
	v_cmp_gt_f32_e32 vcc, s13, v68
	v_mul_f32_e32 v70, 0x4b800000, v68
	s_nop 0
	v_cndmask_b32_e32 v68, v68, v70, vcc
	v_rsq_f32_e32 v68, v68
	s_nop 0
	v_mul_f32_e32 v70, 0x45800000, v68
	v_cndmask_b32_e32 v68, v68, v70, vcc
	v_mad_i64_i32 v[70:71], s[20:21], v69, s9, v[146:147]
	v_lshl_add_u64 v[70:71], v[70:71], 0, v[170:171]
	v_pk_mul_f32 v[66:67], v[66:67], v[68:69] op_sel_hi:[1,0]
	v_pk_mul_f32 v[64:65], v[64:65], v[68:69] op_sel_hi:[1,0]
	v_pk_mul_f32 v[72:73], v[62:63], v[68:69] op_sel_hi:[1,0]
	v_pk_mul_f32 v[62:63], v[60:61], v[68:69] op_sel_hi:[1,0]
	v_cvt_pk_bf16_f32 v60, v64, v65
	v_cvt_pk_bf16_f32 v61, v66, v67
	v_pk_mul_f32 v[58:59], v[58:59], v[68:69] op_sel_hi:[1,0]
	v_cvt_pk_bf16_f32 v62, v62, v63
	v_cvt_pk_bf16_f32 v63, v72, v73
	global_store_dwordx4 v[70:71], v[60:63], off
	v_pk_mul_f32 v[56:57], v[56:57], v[68:69] op_sel_hi:[1,0]
	s_nop 0
	v_pk_mul_f32 v[60:61], v[54:55], v[68:69] op_sel_hi:[1,0]
	v_pk_mul_f32 v[54:55], v[52:53], v[68:69] op_sel_hi:[1,0]
	v_cvt_pk_bf16_f32 v52, v56, v57
	v_cvt_pk_bf16_f32 v53, v58, v59
	s_nop 0
	v_cvt_pk_bf16_f32 v54, v54, v55
	v_cvt_pk_bf16_f32 v55, v60, v61
	global_store_dwordx4 v[70:71], v[52:55], off offset:256
	s_nop 1
	v_mov_b32_e32 v52, v251
	s_nop 0
	v_add_u32_e32 v53, 0x90, v142
	v_fmamk_f32 v52, v52, 0x3a000000, v202
	v_cmp_gt_f32_e32 vcc, s13, v52
	v_mul_f32_e32 v54, 0x4b800000, v52
	s_nop 0
	v_cndmask_b32_e32 v52, v52, v54, vcc
	v_rsq_f32_e32 v52, v52
	s_nop 0
	v_mul_f32_e32 v54, 0x45800000, v52
	v_cndmask_b32_e32 v52, v52, v54, vcc
	v_mad_i64_i32 v[54:55], s[20:21], v53, s9, v[146:147]
	v_lshl_add_u64 v[54:55], v[54:55], 0, v[170:171]
	v_pk_mul_f32 v[50:51], v[50:51], v[52:53] op_sel_hi:[1,0]
	v_pk_mul_f32 v[48:49], v[48:49], v[52:53] op_sel_hi:[1,0]
	v_pk_mul_f32 v[56:57], v[46:47], v[52:53] op_sel_hi:[1,0]
	v_pk_mul_f32 v[46:47], v[44:45], v[52:53] op_sel_hi:[1,0]
	v_cvt_pk_bf16_f32 v44, v48, v49
	v_cvt_pk_bf16_f32 v45, v50, v51
	v_pk_mul_f32 v[42:43], v[42:43], v[52:53] op_sel_hi:[1,0]
	v_cvt_pk_bf16_f32 v46, v46, v47
	v_cvt_pk_bf16_f32 v47, v56, v57
	global_store_dwordx4 v[54:55], v[44:47], off
	v_pk_mul_f32 v[40:41], v[40:41], v[52:53] op_sel_hi:[1,0]
	s_nop 0
	v_pk_mul_f32 v[44:45], v[38:39], v[52:53] op_sel_hi:[1,0]
	v_pk_mul_f32 v[38:39], v[36:37], v[52:53] op_sel_hi:[1,0]
	v_cvt_pk_bf16_f32 v36, v40, v41
	v_cvt_pk_bf16_f32 v37, v42, v43
	s_nop 0
	v_cvt_pk_bf16_f32 v38, v38, v39
	v_cvt_pk_bf16_f32 v39, v44, v45
	global_store_dwordx4 v[54:55], v[36:39], off offset:256
	s_nop 1
	v_mov_b32_e32 v36, v252
	s_nop 0
	v_add_u32_e32 v37, 0xa0, v142
	v_fmamk_f32 v36, v36, 0x3a000000, v202
	v_cmp_gt_f32_e32 vcc, s13, v36
	v_mul_f32_e32 v38, 0x4b800000, v36
	s_nop 0
	v_cndmask_b32_e32 v36, v36, v38, vcc
	v_rsq_f32_e32 v36, v36
	s_nop 0
	v_mul_f32_e32 v38, 0x45800000, v36
	v_cndmask_b32_e32 v36, v36, v38, vcc
	v_mad_i64_i32 v[38:39], s[20:21], v37, s9, v[146:147]
	v_lshl_add_u64 v[38:39], v[38:39], 0, v[170:171]
	v_pk_mul_f32 v[34:35], v[34:35], v[36:37] op_sel_hi:[1,0]
	v_pk_mul_f32 v[32:33], v[32:33], v[36:37] op_sel_hi:[1,0]
	v_pk_mul_f32 v[40:41], v[30:31], v[36:37] op_sel_hi:[1,0]
	v_pk_mul_f32 v[30:31], v[28:29], v[36:37] op_sel_hi:[1,0]
	v_cvt_pk_bf16_f32 v28, v32, v33
	v_cvt_pk_bf16_f32 v29, v34, v35
	v_pk_mul_f32 v[26:27], v[26:27], v[36:37] op_sel_hi:[1,0]
	v_cvt_pk_bf16_f32 v30, v30, v31
	v_cvt_pk_bf16_f32 v31, v40, v41
	global_store_dwordx4 v[38:39], v[28:31], off
	v_pk_mul_f32 v[24:25], v[24:25], v[36:37] op_sel_hi:[1,0]
	s_nop 0
	v_pk_mul_f32 v[28:29], v[22:23], v[36:37] op_sel_hi:[1,0]
	v_pk_mul_f32 v[22:23], v[20:21], v[36:37] op_sel_hi:[1,0]
	v_cvt_pk_bf16_f32 v20, v24, v25
	v_cvt_pk_bf16_f32 v21, v26, v27
	s_nop 0
	v_cvt_pk_bf16_f32 v22, v22, v23
	v_cvt_pk_bf16_f32 v23, v28, v29
	global_store_dwordx4 v[38:39], v[20:23], off offset:256
	s_nop 1
	v_mov_b32_e32 v20, v253
	s_nop 0
	v_add_u32_e32 v21, 0xb0, v142
	v_fmamk_f32 v20, v20, 0x3a000000, v202
	v_cmp_gt_f32_e32 vcc, s13, v20
	v_mul_f32_e32 v22, 0x4b800000, v20
	s_nop 0
	v_cndmask_b32_e32 v20, v20, v22, vcc
	v_rsq_f32_e32 v20, v20
	s_nop 0
	v_mul_f32_e32 v22, 0x45800000, v20
	v_cndmask_b32_e32 v20, v20, v22, vcc
	v_mad_i64_i32 v[22:23], s[20:21], v21, s9, v[146:147]
	v_lshl_add_u64 v[22:23], v[22:23], 0, v[170:171]
	v_pk_mul_f32 v[18:19], v[18:19], v[20:21] op_sel_hi:[1,0]
	v_pk_mul_f32 v[16:17], v[16:17], v[20:21] op_sel_hi:[1,0]
	v_pk_mul_f32 v[24:25], v[14:15], v[20:21] op_sel_hi:[1,0]
	v_pk_mul_f32 v[14:15], v[12:13], v[20:21] op_sel_hi:[1,0]
	v_cvt_pk_bf16_f32 v12, v16, v17
	v_cvt_pk_bf16_f32 v13, v18, v19
	s_and_b64 vcc, exec, s[0:1]
	v_cvt_pk_bf16_f32 v14, v14, v15
	v_cvt_pk_bf16_f32 v15, v24, v25
	global_store_dwordx4 v[22:23], v[12:15], off
	s_mov_b64 s[20:21], s[14:15]
	v_pk_mul_f32 v[10:11], v[10:11], v[20:21] op_sel_hi:[1,0]
	v_pk_mul_f32 v[12:13], v[6:7], v[20:21] op_sel_hi:[1,0]
	v_pk_mul_f32 v[6:7], v[4:5], v[20:21] op_sel_hi:[1,0]
	v_pk_mul_f32 v[8:9], v[8:9], v[20:21] op_sel_hi:[1,0]
	v_cvt_pk_bf16_f32 v5, v10, v11
	v_cvt_pk_bf16_f32 v6, v6, v7
	v_cvt_pk_bf16_f32 v7, v12, v13
	s_nop 0
	v_cvt_pk_bf16_f32 v4, v8, v9
	global_store_dwordx4 v[22:23], v[4:7], off offset:256
	s_cbranch_vccz .LBB0_91
	s_waitcnt vmcnt(0)
	s_mov_b32 s47, s50
	s_cmpk_gt_u32 s27, 0xff
	s_cbranch_scc1 .LBB0_102
	s_barrier

; #define PG8_STAGE(bufoff, gbase, voff) do { _Pragma("unroll") for (int _i = 0; _i < 2; ++_i) \
;         __builtin_amdgcn_global_load_lds((const unsigned*)((const char*)(gbase) + (voff)[_i]), (LAS unsigned*)(lds + (bufoff) + ldsw + _i * 8192), 16, 0, 0); } while (0)
; #define PG8_LDA(dst, b, h) do { _Pragma("unroll") for (int m = 0; m < 4; ++m) _Pragma("unroll") for (int k = 0; k < 2; ++k) dst[m][k] = *(const LAS bf16x8*)(lds + PG8_SA(b, h) + aoff + m * 2048 + k * 1024); } while (0)
; #define PG8_LDB(dst, b, h) do { _Pragma("unroll") for (int n = 0; n < 2; ++n) _Pragma("unroll") for (int k = 0; k < 2; ++k) dst[n][k] = *(const LAS bf16x8*)(lds + PG8_SB(b, h) + boff + n * 2048 + k * 1024); } while (0)
; #define PG8_MMA(ai, bj, At, Bt) do { __builtin_amdgcn_s_setprio(1); _Pragma("unroll") for (int m = 0; m < 4; ++m) _Pragma("unroll") for (int n = 0; n < 2; ++n) _Pragma("unroll") for (int k = 0; k < 2; ++k) \
;         acc[ai][bj][m][n] = __builtin_amdgcn_mfma_f32_16x16x32_bf16(Bt[n][k], At[m][k], acc[ai][bj][m][n], 0, 0, 0); __builtin_amdgcn_s_setprio(0); } while (0)
; #define PG8_BAR __builtin_amdgcn_s_barrier()
; template <class Epi>
; __device__ __forceinline__ void gemm_phase(LAS unsigned char* lds, const Gemm g, const StaticOrder& S, const Epi& E) {
;     ...
;         const bool has_next = S.next(ui + 1, nxt);
;         const char* nA = has_next ? (const char*)g.A + (size_t)nxt.pm * tstep : cA; const char* nB = has_next ? (const char*)g.Bt + (size_t)nxt.pn * tstep : cB;
;         for (int t = 0; t < nt; t += 2) {
;             const bool last = (t == nt - 2);
;             const char* a1 = cA + (size_t)(t + 1) * kstep;
;             const char* a2 = last ? nA : cA + (size_t)(t + 2) * kstep; const char* b2 = last ? nB : cB + (size_t)(t + 2) * kstep;
;             const char* a3 = a2 + kstep; const char* b3 = b2 + kstep;
;             PG8_LDB(B0, 0, 0); PG8_SCHED; PG8_LDA(At, 0, 0); PG8_STAGE(PG8_SA(1, 1), a1 + hstep, voffA);
;             PG8_WAIT_L(8); PG8_BAR; PG8_WAIT_L(0); PG8_MMA(0, 0, At, B0); PG8_BAR; PG8_SCHED;
;     ...
; #pragma unroll
;         for (int a = 0; a < 2; ++a)
; #pragma unroll
;             for (int b = 0; b < 2; ++b)
; #pragma unroll
;                 for (int m = 0; m < 4; ++m)
; #pragma unroll
;                     for (int n = 0; n < 2; ++n) acc[a][b][m][n] = (f32x4){0.f, 0.f, 0.f, 0.f};
;         cur = nxt; cA = nA; cB = nB; ++ui;
.LBB0_216:
	s_ashr_i32 s17, s16, 31
	v_cmp_lt_i64_e32 vcc, s[18:19], v[154:155]
	s_lshl_b64 s[18:19], s[16:17], 21
	s_add_u32 s18, s37, s18
	s_addc_u32 s19, s38, s19
	s_and_b64 s[20:21], vcc, exec
	s_cselect_b32 s17, s19, s27
	s_cselect_b32 s23, s18, s26
	s_ashr_i32 s15, s14, 31
	s_lshl_b64 s[20:21], s[14:15], 21
	s_add_u32 s20, s2, s20
	s_addc_u32 s21, s3, s21
	s_and_b64 s[30:31], vcc, exec
	s_cselect_b32 s15, s21, s29
	s_cselect_b32 s25, s20, s28
	s_add_u32 s26, s26, 0x100080
	s_addc_u32 s27, s27, 0
	s_add_u32 s54, s28, 0x100
	v_mov_b32_e32 v4, 0
	s_addc_u32 s72, s29, 0
	s_mov_b32 s73, -2
	s_waitcnt lgkmcnt(0)
	v_mov_b32_e32 v5, v4
	v_mov_b32_e32 v6, v4
	v_mov_b32_e32 v7, v4
	v_mov_b32_e32 v8, v4
	v_mov_b32_e32 v9, v4
	v_mov_b32_e32 v10, v4
	v_mov_b32_e32 v11, v4
	v_mov_b32_e32 v20, v4
	v_mov_b32_e32 v21, v4
	v_mov_b32_e32 v22, v4
	v_mov_b32_e32 v23, v4
	v_mov_b32_e32 v24, v4
	v_mov_b32_e32 v25, v4
	v_mov_b32_e32 v26, v4
	v_mov_b32_e32 v27, v4
	v_mov_b32_e32 v36, v4
	v_mov_b32_e32 v37, v4
	v_mov_b32_e32 v38, v4
	v_mov_b32_e32 v39, v4
	v_mov_b32_e32 v40, v4
	v_mov_b32_e32 v41, v4
	v_mov_b32_e32 v42, v4
	v_mov_b32_e32 v43, v4
	v_mov_b32_e32 v68, v4
	v_mov_b32_e32 v69, v4
	v_mov_b32_e32 v70, v4
	v_mov_b32_e32 v71, v4
	v_mov_b32_e32 v72, v4
	v_mov_b32_e32 v73, v4
	v_mov_b32_e32 v74, v4
	v_mov_b32_e32 v75, v4
	v_mov_b32_e32 v12, v4
	v_mov_b32_e32 v13, v4
	v_mov_b32_e32 v14, v4
	v_mov_b32_e32 v15, v4
	v_mov_b32_e32 v16, v4
	v_mov_b32_e32 v17, v4
	v_mov_b32_e32 v18, v4
	v_mov_b32_e32 v19, v4
	v_mov_b32_e32 v28, v4
	v_mov_b32_e32 v29, v4
	v_mov_b32_e32 v30, v4
	v_mov_b32_e32 v31, v4
	v_mov_b32_e32 v32, v4
	v_mov_b32_e32 v33, v4
	v_mov_b32_e32 v34, v4
	v_mov_b32_e32 v35, v4
	v_mov_b32_e32 v44, v4
	v_mov_b32_e32 v45, v4
	v_mov_b32_e32 v46, v4
	v_mov_b32_e32 v47, v4
	v_mov_b32_e32 v48, v4
	v_mov_b32_e32 v49, v4
	v_mov_b32_e32 v50, v4
	v_mov_b32_e32 v51, v4
	v_mov_b32_e32 v76, v4
	v_mov_b32_e32 v77, v4
	v_mov_b32_e32 v78, v4
	v_mov_b32_e32 v79, v4
	v_mov_b32_e32 v80, v4
	v_mov_b32_e32 v81, v4
	v_mov_b32_e32 v82, v4
	v_mov_b32_e32 v83, v4
	v_mov_b32_e32 v84, v4
	v_mov_b32_e32 v85, v4
	v_mov_b32_e32 v86, v4
	v_mov_b32_e32 v87, v4
	v_mov_b32_e32 v88, v4
	v_mov_b32_e32 v89, v4
	v_mov_b32_e32 v90, v4
	v_mov_b32_e32 v91, v4
	v_mov_b32_e32 v100, v4
	v_mov_b32_e32 v101, v4
	v_mov_b32_e32 v102, v4
	v_mov_b32_e32 v103, v4
	v_mov_b32_e32 v104, v4
	v_mov_b32_e32 v105, v4
	v_mov_b32_e32 v106, v4
	v_mov_b32_e32 v107, v4
	v_mov_b32_e32 v116, v4
	v_mov_b32_e32 v117, v4
	v_mov_b32_e32 v118, v4
	v_mov_b32_e32 v119, v4
	v_mov_b32_e32 v120, v4
	v_mov_b32_e32 v121, v4
	v_mov_b32_e32 v122, v4
	v_mov_b32_e32 v123, v4
	v_mov_b32_e32 v132, v4
	v_mov_b32_e32 v133, v4
	v_mov_b32_e32 v134, v4
	v_mov_b32_e32 v135, v4
	v_mov_b32_e32 v136, v4
	v_mov_b32_e32 v137, v4
	v_mov_b32_e32 v138, v4
	v_mov_b32_e32 v139, v4
	v_mov_b32_e32 v92, v4
	v_mov_b32_e32 v93, v4
	v_mov_b32_e32 v94, v4
	v_mov_b32_e32 v95, v4
	v_mov_b32_e32 v96, v4
	v_mov_b32_e32 v97, v4
	v_mov_b32_e32 v98, v4
	v_mov_b32_e32 v99, v4
	v_mov_b32_e32 v108, v4
	v_mov_b32_e32 v109, v4
	v_mov_b32_e32 v110, v4
	v_mov_b32_e32 v111, v4
	v_mov_b32_e32 v112, v4
	v_mov_b32_e32 v113, v4
	v_mov_b32_e32 v114, v4
	v_mov_b32_e32 v115, v4
	v_mov_b32_e32 v124, v4
	v_mov_b32_e32 v125, v4
	v_mov_b32_e32 v126, v4
	v_mov_b32_e32 v127, v4
	v_mov_b32_e32 v128, v4
	v_mov_b32_e32 v129, v4
	v_mov_b32_e32 v130, v4
	v_mov_b32_e32 v131, v4
	v_mov_b32_e32 v140, v4
	v_mov_b32_e32 v141, v4
	v_mov_b32_e32 v142, v4
	v_mov_b32_e32 v143, v4
	v_mov_b32_e32 v144, v4
	v_mov_b32_e32 v145, v4
	v_mov_b32_e32 v146, v4
	v_mov_b32_e32 v147, v4
	v_readfirstlane_b32 s98, v151
	s_nop 3
	s_lshr_b32 s98, s98, 8
	s_cmp_lg_u32 s98, 0
	s_cbranch_scc0 .Lprio_skip_217
	s_setprio 1
.Lprio_skip_217:
.LBB0_217:
	s_add_u32 s28, s26, 0xfff00080
	s_addc_u32 s29, s27, -1
	s_add_i32 s74, 0, 0x10000
	v_add_u32_e32 v64, s74, v163
	ds_read_b128 v[52:55], v64
	ds_read_b128 v[56:59], v64 offset:1024
	ds_read_b128 v[60:63], v64 offset:2048
	ds_read_b128 v[64:67], v64 offset:3072
	s_cmp_eq_u32 s73, 60
	s_cselect_b32 s31, s17, s29
	s_cselect_b32 s30, s23, s28
	s_cselect_b32 s29, s15, s72
	s_cselect_b32 s28, s25, s54
	v_lshl_add_u64 v[194:195], s[26:27], 0, v[178:179]
	s_add_i32 m0, s40, 0xc000
	ds_read_b128 v[182:185], v197
	ds_read_b128 v[186:189], v197 offset:1024
	ds_read_b128 v[190:193], v197 offset:2048
	ds_read_b128 v[198:201], v197 offset:3072
	ds_read_b128 v[214:217], v197 offset:4096
	ds_read_b128 v[218:221], v197 offset:5120
	ds_read_b128 v[222:225], v197 offset:6144
	ds_read_b128 v[226:229], v197 offset:7168
	global_load_lds_dwordx4 v[194:195], off
	v_lshl_add_u64 v[194:195], s[26:27], 0, v[180:181]
	s_add_i32 m0, s40, 0xe000
	s_nop 0
	global_load_lds_dwordx4 v[194:195], off
	s_waitcnt lgkmcnt(8)
	s_barrier
	s_waitcnt lgkmcnt(0)
	s_waitcnt lgkmcnt(0)
	v_mfma_f32_16x16x32_bf16 v[144:147], v[52:55], v[182:185], v[144:147]
	v_mfma_f32_16x16x32_bf16 v[140:143], v[60:63], v[182:185], v[140:143]
	v_mfma_f32_16x16x32_bf16 v[128:131], v[52:55], v[190:193], v[128:131]
	v_mfma_f32_16x16x32_bf16 v[124:127], v[60:63], v[190:193], v[124:127]
	v_mfma_f32_16x16x32_bf16 v[112:115], v[52:55], v[214:217], v[112:115]
	v_mfma_f32_16x16x32_bf16 v[108:111], v[60:63], v[214:217], v[108:111]
	v_mfma_f32_16x16x32_bf16 v[96:99], v[52:55], v[222:225], v[96:99]
	v_mfma_f32_16x16x32_bf16 v[92:95], v[60:63], v[222:225], v[92:95]
	v_mfma_f32_16x16x32_bf16 v[144:147], v[56:59], v[186:189], v[144:147]
	v_mfma_f32_16x16x32_bf16 v[140:143], v[64:67], v[186:189], v[140:143]
	v_mfma_f32_16x16x32_bf16 v[128:131], v[56:59], v[198:201], v[128:131]
	v_mfma_f32_16x16x32_bf16 v[124:127], v[64:67], v[198:201], v[124:127]
	v_mfma_f32_16x16x32_bf16 v[112:115], v[56:59], v[218:221], v[112:115]
	v_mfma_f32_16x16x32_bf16 v[108:111], v[64:67], v[218:221], v[108:111]
	v_mfma_f32_16x16x32_bf16 v[96:99], v[56:59], v[226:229], v[96:99]
	v_mfma_f32_16x16x32_bf16 v[92:95], v[64:67], v[226:229], v[92:95]
	s_barrier
; #define PG8_STAGE(bufoff, gbase, voff) do { _Pragma("unroll") for (int _i = 0; _i < 2; ++_i) \
;         __builtin_amdgcn_global_load_lds((const unsigned*)((const char*)(gbase) + (voff)[_i]), (LAS unsigned*)(lds + (bufoff) + ldsw + _i * 8192), 16, 0, 0); } while (0)
; #define PG8_LDA(dst, b, h) do { _Pragma("unroll") for (int m = 0; m < 4; ++m) _Pragma("unroll") for (int k = 0; k < 2; ++k) dst[m][k] = *(const LAS bf16x8*)(lds + PG8_SA(b, h) + aoff + m * 2048 + k * 1024); } while (0)
; #define PG8_LDB(dst, b, h) do { _Pragma("unroll") for (int n = 0; n < 2; ++n) _Pragma("unroll") for (int k = 0; k < 2; ++k) dst[n][k] = *(const LAS bf16x8*)(lds + PG8_SB(b, h) + boff + n * 2048 + k * 1024); } while (0)
; #define PG8_MMA(ai, bj, At, Bt) do { __builtin_amdgcn_s_setprio(1); _Pragma("unroll") for (int m = 0; m < 4; ++m) _Pragma("unroll") for (int n = 0; n < 2; ++n) _Pragma("unroll") for (int k = 0; k < 2; ++k) \
;         acc[ai][bj][m][n] = __builtin_amdgcn_mfma_f32_16x16x32_bf16(Bt[n][k], At[m][k], acc[ai][bj][m][n], 0, 0, 0); __builtin_amdgcn_s_setprio(0); } while (0)
; #define PG8_WAIT_V(n) asm volatile("s_waitcnt vmcnt(" #n ")" ::: "memory")
; #define PG8_WAIT_L(n) asm volatile("s_waitcnt lgkmcnt(" #n ")" ::: "memory")
; #define PG8_BAR __builtin_amdgcn_s_barrier()
; #define PG8_SCHED __builtin_amdgcn_sched_barrier(0)
; template <class Epi>
; __device__ __forceinline__ void gemm_phase(LAS unsigned char* lds, const Gemm g, const StaticOrder& S, const Epi& E) {
;     ...
;             PG8_LDB(B1, 0, 1); PG8_STAGE(PG8_SB(0, 0), b2, voffB);
;             PG8_BAR; PG8_WAIT_L(0); PG8_MMA(0, 1, At, B1); PG8_BAR;
;             PG8_LDA(At, 0, 1); PG8_STAGE(PG8_SA(0, 0), a2, voffA);
;             PG8_BAR; PG8_WAIT_L(0); PG8_MMA(1, 0, At, B0); PG8_BAR; PG8_SCHED;
;             PG8_STAGE(PG8_SB(0, 1), b2 + hstep, voffB);
;             PG8_WAIT_V(6); PG8_BAR; PG8_MMA(1, 1, At, B1); PG8_BAR;
;             PG8_LDB(B0, 1, 0); PG8_SCHED; PG8_LDA(At, 1, 0); PG8_STAGE(PG8_SA(0, 1), a2 + hstep, voffA);
;             PG8_WAIT_L(8); PG8_BAR; PG8_WAIT_L(0); PG8_MMA(0, 0, At, B0); PG8_BAR; PG8_SCHED;
	s_add_i32 s76, 0, 0x14000
	s_add_i32 s74, s74, s39
	v_add_u32_e32 v148, s76, v163
	v_lshl_add_u64 v[194:195], s[28:29], 0, v[172:173]
	s_mov_b32 m0, s74
	ds_read_b128 v[230:233], v148
	ds_read_b128 v[234:237], v148 offset:1024
	ds_read_b128 v[238:241], v148 offset:2048
	ds_read_b128 v[242:245], v148 offset:3072
	global_load_lds_dwordx4 v[194:195], off
	v_lshl_add_u64 v[246:247], s[28:29], 0, v[176:177]
	s_add_i32 m0, s74, 0x2000
	s_nop 0
	global_load_lds_dwordx4 v[246:247], off
	s_barrier
	s_waitcnt lgkmcnt(0)
	s_waitcnt lgkmcnt(0)
	v_mfma_f32_16x16x32_bf16 v[136:139], v[230:233], v[182:185], v[136:139]
	v_mfma_f32_16x16x32_bf16 v[132:135], v[238:241], v[182:185], v[132:135]
	v_mfma_f32_16x16x32_bf16 v[120:123], v[230:233], v[190:193], v[120:123]
	v_mfma_f32_16x16x32_bf16 v[116:119], v[238:241], v[190:193], v[116:119]
	v_mfma_f32_16x16x32_bf16 v[104:107], v[230:233], v[214:217], v[104:107]
	v_mfma_f32_16x16x32_bf16 v[100:103], v[238:241], v[214:217], v[100:103]
	v_mfma_f32_16x16x32_bf16 v[88:91], v[230:233], v[222:225], v[88:91]
	v_mfma_f32_16x16x32_bf16 v[84:87], v[238:241], v[222:225], v[84:87]
	v_mfma_f32_16x16x32_bf16 v[136:139], v[234:237], v[186:189], v[136:139]
	v_mfma_f32_16x16x32_bf16 v[132:135], v[242:245], v[186:189], v[132:135]
	v_mfma_f32_16x16x32_bf16 v[120:123], v[234:237], v[198:201], v[120:123]
	v_mfma_f32_16x16x32_bf16 v[116:119], v[242:245], v[198:201], v[116:119]
	v_mfma_f32_16x16x32_bf16 v[104:107], v[234:237], v[218:221], v[104:107]
	v_mfma_f32_16x16x32_bf16 v[100:103], v[242:245], v[218:221], v[100:103]
	v_mfma_f32_16x16x32_bf16 v[88:91], v[234:237], v[226:229], v[88:91]
	v_mfma_f32_16x16x32_bf16 v[84:87], v[242:245], v[226:229], v[84:87]
	s_mov_b32 m0, s40
	v_lshl_add_u64 v[248:249], s[30:31], 0, v[170:171]
	s_barrier
	ds_read_b128 v[182:185], v197 offset:16384
	ds_read_b128 v[186:189], v197 offset:17408
	ds_read_b128 v[190:193], v197 offset:18432
	ds_read_b128 v[198:201], v197 offset:19456
	ds_read_b128 v[214:217], v197 offset:20480
	ds_read_b128 v[218:221], v197 offset:21504
	ds_read_b128 v[222:225], v197 offset:22528
	ds_read_b128 v[226:229], v197 offset:23552
	global_load_lds_dwordx4 v[248:249], off
	v_lshl_add_u64 v[250:251], s[30:31], 0, v[174:175]
	s_mov_b32 m0, s41
	s_nop 0
	global_load_lds_dwordx4 v[250:251], off
	s_barrier
	s_waitcnt lgkmcnt(0)
	s_waitcnt lgkmcnt(0)
	v_mfma_f32_16x16x32_bf16 v[80:83], v[52:55], v[182:185], v[80:83]
	v_mfma_f32_16x16x32_bf16 v[76:79], v[60:63], v[182:185], v[76:79]
	v_mfma_f32_16x16x32_bf16 v[48:51], v[52:55], v[190:193], v[48:51]
	v_mfma_f32_16x16x32_bf16 v[44:47], v[60:63], v[190:193], v[44:47]
	v_mfma_f32_16x16x32_bf16 v[32:35], v[52:55], v[214:217], v[32:35]
	v_mfma_f32_16x16x32_bf16 v[28:31], v[60:63], v[214:217], v[28:31]
	v_mfma_f32_16x16x32_bf16 v[16:19], v[52:55], v[222:225], v[16:19]
	v_mfma_f32_16x16x32_bf16 v[12:15], v[60:63], v[222:225], v[12:15]
	v_mfma_f32_16x16x32_bf16 v[80:83], v[56:59], v[186:189], v[80:83]
	v_mfma_f32_16x16x32_bf16 v[76:79], v[64:67], v[186:189], v[76:79]
	v_mfma_f32_16x16x32_bf16 v[48:51], v[56:59], v[198:201], v[48:51]
	v_mfma_f32_16x16x32_bf16 v[44:47], v[64:67], v[198:201], v[44:47]
	v_mfma_f32_16x16x32_bf16 v[32:35], v[56:59], v[218:221], v[32:35]
	v_mfma_f32_16x16x32_bf16 v[28:31], v[64:67], v[218:221], v[28:31]
	v_mfma_f32_16x16x32_bf16 v[16:19], v[56:59], v[226:229], v[16:19]
	v_mfma_f32_16x16x32_bf16 v[12:15], v[64:67], v[226:229], v[12:15]
	s_barrier
	s_add_u32 s74, s28, 0x100000
	s_addc_u32 s75, s29, 0
	s_add_i32 s76, s76, s39
	v_lshl_add_u64 v[52:53], s[74:75], 0, v[172:173]
	s_mov_b32 m0, s76
	s_nop 0
	global_load_lds_dwordx4 v[52:53], off
	v_lshl_add_u64 v[52:53], s[74:75], 0, v[176:177]
	s_add_i32 m0, s76, 0x2000
	s_nop 0
	global_load_lds_dwordx4 v[52:53], off
	s_waitcnt vmcnt(6)
	s_barrier
	v_mfma_f32_16x16x32_bf16 v[40:43], v[230:233], v[190:193], v[40:43]
	v_mfma_f32_16x16x32_bf16 v[36:39], v[238:241], v[190:193], v[36:39]
	v_mfma_f32_16x16x32_bf16 v[24:27], v[230:233], v[214:217], v[24:27]
	v_mfma_f32_16x16x32_bf16 v[20:23], v[238:241], v[214:217], v[20:23]
	v_mfma_f32_16x16x32_bf16 v[8:11], v[230:233], v[222:225], v[8:11]
	v_mfma_f32_16x16x32_bf16 v[4:7], v[238:241], v[222:225], v[4:7]
	v_mfma_f32_16x16x32_bf16 v[52:55], v[230:233], v[182:185], v[72:75]
	v_mfma_f32_16x16x32_bf16 v[56:59], v[238:241], v[182:185], v[68:71]
	v_mfma_f32_16x16x32_bf16 v[40:43], v[234:237], v[198:201], v[40:43]
	v_mfma_f32_16x16x32_bf16 v[36:39], v[242:245], v[198:201], v[36:39]
	v_mfma_f32_16x16x32_bf16 v[24:27], v[234:237], v[218:221], v[24:27]
	v_mfma_f32_16x16x32_bf16 v[20:23], v[242:245], v[218:221], v[20:23]
	v_mfma_f32_16x16x32_bf16 v[8:11], v[234:237], v[226:229], v[8:11]
	v_mfma_f32_16x16x32_bf16 v[4:7], v[242:245], v[226:229], v[4:7]
	v_mfma_f32_16x16x32_bf16 v[52:55], v[234:237], v[186:189], v[52:55]
	v_mfma_f32_16x16x32_bf16 v[56:59], v[242:245], v[186:189], v[56:59]
	s_add_i32 s74, 0, 0x18000
	v_add_u32_e32 v72, s74, v163
	s_barrier
	ds_read_b128 v[60:63], v72
	ds_read_b128 v[64:67], v72 offset:1024
	ds_read_b128 v[68:71], v72 offset:2048
	ds_read_b128 v[72:75], v72 offset:3072
	s_add_u32 s30, s30, 0x100000
	s_addc_u32 s31, s31, 0
	s_mov_b32 m0, s42
	v_lshl_add_u64 v[230:231], s[30:31], 0, v[170:171]
	ds_read_b128 v[182:185], v197 offset:32768
	ds_read_b128 v[186:189], v197 offset:33792
	ds_read_b128 v[190:193], v197 offset:34816
	ds_read_b128 v[198:201], v197 offset:35840
	ds_read_b128 v[214:217], v197 offset:36864
	ds_read_b128 v[218:221], v197 offset:37888
	ds_read_b128 v[222:225], v197 offset:38912
	ds_read_b128 v[226:229], v197 offset:39936
	global_load_lds_dwordx4 v[230:231], off
	v_lshl_add_u64 v[230:231], s[30:31], 0, v[174:175]
	s_mov_b32 m0, s43
	s_nop 0
	global_load_lds_dwordx4 v[230:231], off
	s_waitcnt lgkmcnt(8)
	s_barrier
; #define PG8_STAGE(bufoff, gbase, voff) do { _Pragma("unroll") for (int _i = 0; _i < 2; ++_i) \
;         __builtin_amdgcn_global_load_lds((const unsigned*)((const char*)(gbase) + (voff)[_i]), (LAS unsigned*)(lds + (bufoff) + ldsw + _i * 8192), 16, 0, 0); } while (0)
; #define PG8_LDA(dst, b, h) do { _Pragma("unroll") for (int m = 0; m < 4; ++m) _Pragma("unroll") for (int k = 0; k < 2; ++k) dst[m][k] = *(const LAS bf16x8*)(lds + PG8_SA(b, h) + aoff + m * 2048 + k * 1024); } while (0)
; #define PG8_LDB(dst, b, h) do { _Pragma("unroll") for (int n = 0; n < 2; ++n) _Pragma("unroll") for (int k = 0; k < 2; ++k) dst[n][k] = *(const LAS bf16x8*)(lds + PG8_SB(b, h) + boff + n * 2048 + k * 1024); } while (0)
; #define PG8_MMA(ai, bj, At, Bt) do { __builtin_amdgcn_s_setprio(1); _Pragma("unroll") for (int m = 0; m < 4; ++m) _Pragma("unroll") for (int n = 0; n < 2; ++n) _Pragma("unroll") for (int k = 0; k < 2; ++k) \
;         acc[ai][bj][m][n] = __builtin_amdgcn_mfma_f32_16x16x32_bf16(Bt[n][k], At[m][k], acc[ai][bj][m][n], 0, 0, 0); __builtin_amdgcn_s_setprio(0); } while (0)
; #define PG8_WAIT_L(n) asm volatile("s_waitcnt lgkmcnt(" #n ")" ::: "memory")
; #define PG8_BAR __builtin_amdgcn_s_barrier()
; #define PG8_SCHED __builtin_amdgcn_sched_barrier(0)
; template <class Epi>
; __device__ __forceinline__ void gemm_phase(LAS unsigned char* lds, const Gemm g, const StaticOrder& S, const Epi& E) {
;     ...
;             PG8_WAIT_L(8); PG8_BAR; PG8_WAIT_L(0); PG8_MMA(0, 0, At, B0); PG8_BAR; PG8_SCHED;
;             PG8_LDB(B1, 1, 1); PG8_STAGE(PG8_SB(1, 0), b3, voffB);
;             PG8_BAR; PG8_WAIT_L(0); PG8_MMA(0, 1, At, B1); PG8_BAR;
;             PG8_LDA(At, 1, 1); PG8_STAGE(PG8_SA(1, 0), a3, voffA);
;             PG8_BAR; PG8_WAIT_L(0); PG8_MMA(1, 0, At, B0); PG8_BAR; PG8_SCHED;
	s_waitcnt lgkmcnt(0)
	s_waitcnt lgkmcnt(0)
	v_mfma_f32_16x16x32_bf16 v[144:147], v[60:63], v[182:185], v[144:147]
	v_mfma_f32_16x16x32_bf16 v[140:143], v[68:71], v[182:185], v[140:143]
	v_mfma_f32_16x16x32_bf16 v[128:131], v[60:63], v[190:193], v[128:131]
	v_mfma_f32_16x16x32_bf16 v[124:127], v[68:71], v[190:193], v[124:127]
	v_mfma_f32_16x16x32_bf16 v[112:115], v[60:63], v[214:217], v[112:115]
	v_mfma_f32_16x16x32_bf16 v[108:111], v[68:71], v[214:217], v[108:111]
	v_mfma_f32_16x16x32_bf16 v[96:99], v[60:63], v[222:225], v[96:99]
	v_mfma_f32_16x16x32_bf16 v[92:95], v[68:71], v[222:225], v[92:95]
	v_mfma_f32_16x16x32_bf16 v[144:147], v[64:67], v[186:189], v[144:147]
	v_mfma_f32_16x16x32_bf16 v[140:143], v[72:75], v[186:189], v[140:143]
	v_mfma_f32_16x16x32_bf16 v[128:131], v[64:67], v[198:201], v[128:131]
	v_mfma_f32_16x16x32_bf16 v[124:127], v[72:75], v[198:201], v[124:127]
	v_mfma_f32_16x16x32_bf16 v[112:115], v[64:67], v[218:221], v[112:115]
	v_mfma_f32_16x16x32_bf16 v[108:111], v[72:75], v[218:221], v[108:111]
	v_mfma_f32_16x16x32_bf16 v[96:99], v[64:67], v[226:229], v[96:99]
	v_mfma_f32_16x16x32_bf16 v[92:95], v[72:75], v[226:229], v[92:95]
	s_barrier
	s_add_i32 s30, 0, 0x1c000
	s_add_i32 s31, s74, s39
	v_add_u32_e32 v148, s30, v163
	v_lshl_add_u64 v[194:195], v[194:195], 0, s[34:35]
	s_mov_b32 m0, s31
	ds_read_b128 v[230:233], v148
	ds_read_b128 v[234:237], v148 offset:1024
	ds_read_b128 v[238:241], v148 offset:2048
	ds_read_b128 v[242:245], v148 offset:3072
	global_load_lds_dwordx4 v[194:195], off
	v_lshl_add_u64 v[194:195], v[246:247], 0, s[34:35]
	s_add_i32 m0, s31, 0x2000
	s_nop 0
	global_load_lds_dwordx4 v[194:195], off
	s_barrier
	s_waitcnt lgkmcnt(0)
	s_waitcnt lgkmcnt(0)
	v_mfma_f32_16x16x32_bf16 v[136:139], v[230:233], v[182:185], v[136:139]
	v_mfma_f32_16x16x32_bf16 v[132:135], v[238:241], v[182:185], v[132:135]
	v_mfma_f32_16x16x32_bf16 v[120:123], v[230:233], v[190:193], v[120:123]
	v_mfma_f32_16x16x32_bf16 v[116:119], v[238:241], v[190:193], v[116:119]
	v_mfma_f32_16x16x32_bf16 v[104:107], v[230:233], v[214:217], v[104:107]
	v_mfma_f32_16x16x32_bf16 v[100:103], v[238:241], v[214:217], v[100:103]
	v_mfma_f32_16x16x32_bf16 v[88:91], v[230:233], v[222:225], v[88:91]
	v_mfma_f32_16x16x32_bf16 v[84:87], v[238:241], v[222:225], v[84:87]
	v_mfma_f32_16x16x32_bf16 v[136:139], v[234:237], v[186:189], v[136:139]
	v_mfma_f32_16x16x32_bf16 v[132:135], v[242:245], v[186:189], v[132:135]
	v_mfma_f32_16x16x32_bf16 v[120:123], v[234:237], v[198:201], v[120:123]
	v_mfma_f32_16x16x32_bf16 v[116:119], v[242:245], v[198:201], v[116:119]
	v_mfma_f32_16x16x32_bf16 v[104:107], v[234:237], v[218:221], v[104:107]
	v_mfma_f32_16x16x32_bf16 v[100:103], v[242:245], v[218:221], v[100:103]
	v_mfma_f32_16x16x32_bf16 v[88:91], v[234:237], v[226:229], v[88:91]
	v_mfma_f32_16x16x32_bf16 v[84:87], v[242:245], v[226:229], v[84:87]
	s_mov_b32 m0, s46
	v_lshl_add_u64 v[194:195], v[248:249], 0, s[34:35]
	s_barrier
	ds_read_b128 v[182:185], v197 offset:49152
	ds_read_b128 v[186:189], v197 offset:50176
	ds_read_b128 v[190:193], v197 offset:51200
	ds_read_b128 v[198:201], v197 offset:52224
	ds_read_b128 v[214:217], v197 offset:53248
	ds_read_b128 v[218:221], v197 offset:54272
	ds_read_b128 v[222:225], v197 offset:55296
	ds_read_b128 v[226:229], v197 offset:56320
	global_load_lds_dwordx4 v[194:195], off
	v_lshl_add_u64 v[194:195], v[250:251], 0, s[34:35]
	s_mov_b32 m0, s47
	s_nop 0
	global_load_lds_dwordx4 v[194:195], off
	s_barrier
	s_waitcnt lgkmcnt(0)
	s_waitcnt lgkmcnt(0)
	v_mfma_f32_16x16x32_bf16 v[80:83], v[60:63], v[182:185], v[80:83]
	v_mfma_f32_16x16x32_bf16 v[76:79], v[68:71], v[182:185], v[76:79]
	v_mfma_f32_16x16x32_bf16 v[48:51], v[60:63], v[190:193], v[48:51]
	v_mfma_f32_16x16x32_bf16 v[44:47], v[68:71], v[190:193], v[44:47]
	v_mfma_f32_16x16x32_bf16 v[32:35], v[60:63], v[214:217], v[32:35]
	v_mfma_f32_16x16x32_bf16 v[28:31], v[68:71], v[214:217], v[28:31]
	v_mfma_f32_16x16x32_bf16 v[16:19], v[60:63], v[222:225], v[16:19]
	v_mfma_f32_16x16x32_bf16 v[12:15], v[68:71], v[222:225], v[12:15]
	v_mfma_f32_16x16x32_bf16 v[80:83], v[64:67], v[186:189], v[80:83]
	v_mfma_f32_16x16x32_bf16 v[76:79], v[72:75], v[186:189], v[76:79]
	v_mfma_f32_16x16x32_bf16 v[48:51], v[64:67], v[198:201], v[48:51]
	v_mfma_f32_16x16x32_bf16 v[44:47], v[72:75], v[198:201], v[44:47]
	v_mfma_f32_16x16x32_bf16 v[32:35], v[64:67], v[218:221], v[32:35]
	v_mfma_f32_16x16x32_bf16 v[28:31], v[72:75], v[218:221], v[28:31]
	v_mfma_f32_16x16x32_bf16 v[16:19], v[64:67], v[226:229], v[16:19]
	v_mfma_f32_16x16x32_bf16 v[12:15], v[72:75], v[226:229], v[12:15]
	s_barrier
; #define PG8_STAGE(bufoff, gbase, voff) do { _Pragma("unroll") for (int _i = 0; _i < 2; ++_i) \
;         __builtin_amdgcn_global_load_lds((const unsigned*)((const char*)(gbase) + (voff)[_i]), (LAS unsigned*)(lds + (bufoff) + ldsw + _i * 8192), 16, 0, 0); } while (0)
; #define PG8_MMA(ai, bj, At, Bt) do { __builtin_amdgcn_s_setprio(1); _Pragma("unroll") for (int m = 0; m < 4; ++m) _Pragma("unroll") for (int n = 0; n < 2; ++n) _Pragma("unroll") for (int k = 0; k < 2; ++k) \
;         acc[ai][bj][m][n] = __builtin_amdgcn_mfma_f32_16x16x32_bf16(Bt[n][k], At[m][k], acc[ai][bj][m][n], 0, 0, 0); __builtin_amdgcn_s_setprio(0); } while (0)
; #define PG8_WAIT_V(n) asm volatile("s_waitcnt vmcnt(" #n ")" ::: "memory")
; #define PG8_BAR __builtin_amdgcn_s_barrier()
; template <class Epi>
; __device__ __forceinline__ void gemm_phase(LAS unsigned char* lds, const Gemm g, const StaticOrder& S, const Epi& E) {
;     ...
;             PG8_STAGE(PG8_SB(1, 1), b3 + hstep, voffB);
;             PG8_WAIT_V(6); PG8_BAR; PG8_MMA(1, 1, At, B1); PG8_BAR;
;     __device__ __forceinline__ void operator()(const AccT& acc, const pg8::Unit& u, int wr, int wc, int fr, int fq) const {
;         float* H1 = (float*)(p.ws + WS_H1); bf16_t* A2 = (bf16_t*)(p.ws + WS_A2); float* SS2 = (float*)(p.ws + WS_SS2);
;         const float* nw = p.in[21];
;         const int row0 = u.pm * 256 + wr * 64 + fr, col0 = u.pn * 256 + wc * 32 + 8 * fq;
;         f32x4 w[2][2];
; #pragma unroll
;         for (int bj = 0; bj < 2; ++bj) { w[bj][0] = *(const f32x4*)(nw + col0 + bj * 128); w[bj][1] = *(const f32x4*)(nw + col0 + bj * 128 + 4); }
; #pragma unroll
;         for (int ai = 0; ai < 2; ++ai)
; #pragma unroll
;             for (int m = 0; m < 4; ++m) {
;                 const int row = row0 + ai * 128 + m * 16;
;                 const float* rp = resid_row(p, row);
;                 float ss = 0.f;
; #pragma unroll
;                 for (int bj = 0; bj < 2; ++bj) {
;                     f32x4 v0 = acc[ai][bj][m][0], v1 = acc[ai][bj][m][1];
;                     if (rp) { v0 += __builtin_nontemporal_load((const f32x4*)(rp + col0 + bj * 128)); v1 += __builtin_nontemporal_load((const f32x4*)(rp + col0 + bj * 128 + 4)); }
	s_add_u32 s28, s28, 0x100080
	s_addc_u32 s29, s29, 0
	s_add_i32 s30, s30, s39
	v_lshl_add_u64 v[60:61], s[28:29], 0, v[172:173]
	s_mov_b32 m0, s30
	s_nop 0
	global_load_lds_dwordx4 v[60:61], off
	v_lshl_add_u64 v[60:61], s[28:29], 0, v[176:177]
	s_add_i32 m0, s30, 0x2000
	s_nop 0
	global_load_lds_dwordx4 v[60:61], off
	s_waitcnt vmcnt(6)
	s_barrier
	v_mfma_f32_16x16x32_bf16 v[52:55], v[230:233], v[182:185], v[52:55]
	v_mfma_f32_16x16x32_bf16 v[72:75], v[234:237], v[186:189], v[52:55]
	v_mfma_f32_16x16x32_bf16 v[52:55], v[238:241], v[182:185], v[56:59]
	v_mfma_f32_16x16x32_bf16 v[40:43], v[230:233], v[190:193], v[40:43]
	v_mfma_f32_16x16x32_bf16 v[36:39], v[238:241], v[190:193], v[36:39]
	v_mfma_f32_16x16x32_bf16 v[24:27], v[230:233], v[214:217], v[24:27]
	v_mfma_f32_16x16x32_bf16 v[20:23], v[238:241], v[214:217], v[20:23]
	v_mfma_f32_16x16x32_bf16 v[8:11], v[230:233], v[222:225], v[8:11]
	v_mfma_f32_16x16x32_bf16 v[4:7], v[238:241], v[222:225], v[4:7]
	v_mfma_f32_16x16x32_bf16 v[68:71], v[242:245], v[186:189], v[52:55]
	v_mfma_f32_16x16x32_bf16 v[40:43], v[234:237], v[198:201], v[40:43]
	v_mfma_f32_16x16x32_bf16 v[36:39], v[242:245], v[198:201], v[36:39]
	v_mfma_f32_16x16x32_bf16 v[24:27], v[234:237], v[218:221], v[24:27]
	v_mfma_f32_16x16x32_bf16 v[20:23], v[242:245], v[218:221], v[20:23]
	v_mfma_f32_16x16x32_bf16 v[8:11], v[234:237], v[226:229], v[8:11]
	v_mfma_f32_16x16x32_bf16 v[4:7], v[242:245], v[226:229], v[4:7]
	s_add_i32 s73, s73, 2
	s_add_u32 s26, s26, 0x100
	s_addc_u32 s27, s27, 0
	s_add_u32 s54, s54, 0x100
	s_addc_u32 s72, s72, 0
	s_cmp_gt_u32 s73, 61
	s_barrier
	s_cbranch_scc0 .LBB0_217
	s_setprio 0
	v_readlane_b32 s56, v255, 11
	v_lshl_or_b32 v182, s24, 8, v196
	v_ashrrev_i32_e32 v183, 31, v182
	v_readlane_b32 s66, v255, 21
	v_readlane_b32 s67, v255, 22
	s_lshl_b32 s15, s22, 8
	s_add_i32 s15, s15, s44
	v_lshl_add_u64 v[56:57], v[182:183], 2, s[66:67]
	global_load_dwordx4 v[60:63], v[56:57], off offset:16
	global_load_dwordx4 v[64:67], v[56:57], off
	global_load_dwordx4 v[52:55], v[56:57], off offset:528
	s_nop 0
	global_load_dwordx4 v[56:59], v[56:57], off offset:512
	v_or_b32_e32 v184, s15, v153
	v_lshlrev_b32_e32 v148, 11, v184
	s_movk_i32 s17, 0x1fff
	v_and_b32_e32 v198, 0x7800, v148
	v_cmp_lt_i32_e32 vcc, s17, v184
	v_readlane_b32 s57, v255, 12
	v_readlane_b32 s58, v255, 13
	v_readlane_b32 s59, v255, 14
	v_readlane_b32 s60, v255, 15
	v_readlane_b32 s61, v255, 16
	v_readlane_b32 s62, v255, 17
	v_readlane_b32 s63, v255, 18
	v_readlane_b32 s64, v255, 19
	v_readlane_b32 s65, v255, 20
	v_readlane_b32 s68, v255, 23
	v_readlane_b32 s69, v255, 24
	v_readlane_b32 s70, v255, 25
	v_readlane_b32 s71, v255, 26
	s_and_saveexec_b64 s[22:23], vcc
	s_xor_b64 s[22:23], exec, s[22:23]
	s_cbranch_execz .LBB0_223
	s_cmpk_gt_u32 s15, 0x23ff
	s_mov_b64 s[24:25], -1
	s_cbranch_scc0 .LBB0_221
	v_readlane_b32 s56, v254, 59
	s_cmpk_lt_u32 s15, 0x2440
	v_lshlrev_b32_e32 v148, 2, v198
	v_readlane_b32 s57, v254, 60
	s_cselect_b64 vcc, -1, 0
	v_readlane_b32 s58, v254, 61
	v_lshl_add_u64 v[186:187], s[56:57], 0, v[148:149]
	v_readlane_b32 s59, v254, 62
	v_readlane_b32 s60, v254, 63
	v_readlane_b32 s61, v255, 0
	v_readlane_b32 s62, v255, 1
	v_readlane_b32 s63, v255, 2
	v_readlane_b32 s64, v255, 3
	v_readlane_b32 s65, v255, 4
	v_readlane_b32 s66, v255, 5
	v_readlane_b32 s67, v255, 6
	v_readlane_b32 s68, v255, 7
	v_readlane_b32 s69, v255, 8
	v_readlane_b32 s70, v255, 9
	v_readlane_b32 s71, v255, 10
	v_cndmask_b32_e32 v187, 0, v187, vcc
	v_cndmask_b32_e32 v186, 0, v186, vcc
	s_mov_b64 s[24:25], 0

; #define PG8_STAGE(bufoff, gbase, voff) do { _Pragma("unroll") for (int _i = 0; _i < 2; ++_i) \
;         __builtin_amdgcn_global_load_lds((const unsigned*)((const char*)(gbase) + (voff)[_i]), (LAS unsigned*)(lds + (bufoff) + ldsw + _i * 8192), 16, 0, 0); } while (0)
; #define PG8_LDA(dst, b, h) do { _Pragma("unroll") for (int m = 0; m < 4; ++m) _Pragma("unroll") for (int k = 0; k < 2; ++k) dst[m][k] = *(const LAS bf16x8*)(lds + PG8_SA(b, h) + aoff + m * 2048 + k * 1024); } while (0)
; #define PG8_LDB(dst, b, h) do { _Pragma("unroll") for (int n = 0; n < 2; ++n) _Pragma("unroll") for (int k = 0; k < 2; ++k) dst[n][k] = *(const LAS bf16x8*)(lds + PG8_SB(b, h) + boff + n * 2048 + k * 1024); } while (0)
; #define PG8_MMA(ai, bj, At, Bt) do { __builtin_amdgcn_s_setprio(1); _Pragma("unroll") for (int m = 0; m < 4; ++m) _Pragma("unroll") for (int n = 0; n < 2; ++n) _Pragma("unroll") for (int k = 0; k < 2; ++k) \
;         acc[ai][bj][m][n] = __builtin_amdgcn_mfma_f32_16x16x32_bf16(Bt[n][k], At[m][k], acc[ai][bj][m][n], 0, 0, 0); __builtin_amdgcn_s_setprio(0); } while (0)
; #define PG8_BAR __builtin_amdgcn_s_barrier()
; template <class Epi>
; __device__ __forceinline__ void gemm_phase(LAS unsigned char* lds, const Gemm g, const StaticOrder& S, const Epi& E) {
;     ...
;         const bool has_next = S.next(ui + 1, nxt);
;         const char* nA = has_next ? (const char*)g.A + (size_t)nxt.pm * tstep : cA; const char* nB = has_next ? (const char*)g.Bt + (size_t)nxt.pn * tstep : cB;
;         for (int t = 0; t < nt; t += 2) {
;             const bool last = (t == nt - 2);
;             const char* a1 = cA + (size_t)(t + 1) * kstep;
;             const char* a2 = last ? nA : cA + (size_t)(t + 2) * kstep; const char* b2 = last ? nB : cB + (size_t)(t + 2) * kstep;
;             const char* a3 = a2 + kstep; const char* b3 = b2 + kstep;
;             PG8_LDB(B0, 0, 0); PG8_SCHED; PG8_LDA(At, 0, 0); PG8_STAGE(PG8_SA(1, 1), a1 + hstep, voffA);
;             PG8_WAIT_L(8); PG8_BAR; PG8_WAIT_L(0); PG8_MMA(0, 0, At, B0); PG8_BAR; PG8_SCHED;
;     ...
; #pragma unroll
;         for (int a = 0; a < 2; ++a)
; #pragma unroll
;             for (int b = 0; b < 2; ++b)
; #pragma unroll
;                 for (int m = 0; m < 4; ++m)
; #pragma unroll
;                     for (int n = 0; n < 2; ++n) acc[a][b][m][n] = (f32x4){0.f, 0.f, 0.f, 0.f};
;         cur = nxt; cA = nA; cB = nB; ++ui;
.LBB0_757:
	s_ashr_i32 s15, s14, 31
	v_cmp_lt_i64_e32 vcc, s[16:17], v[168:169]
	s_lshl_b64 s[16:17], s[14:15], 20
	s_add_u32 s16, s28, s16
	s_addc_u32 s17, s29, s17
	s_and_b64 s[18:19], vcc, exec
	s_cselect_b32 s15, s17, s21
	s_cselect_b32 s42, s16, s20
	s_ashr_i32 s13, s12, 31
	s_lshl_b64 s[18:19], s[12:13], 20
	s_add_u32 s18, s82, s18
	s_addc_u32 s19, s83, s19
	s_and_b64 s[24:25], vcc, exec
	s_cselect_b32 s13, s19, s23
	s_cselect_b32 s43, s18, s22
	s_add_u32 s20, s20, 0x80080
	s_addc_u32 s21, s21, 0
	s_add_u32 s44, s22, 0x100
	v_mov_b32_e32 v4, 0
	s_addc_u32 s46, s23, 0
	s_mov_b32 s47, -2
	v_mov_b32_e32 v5, v4
	v_mov_b32_e32 v6, v4
	v_mov_b32_e32 v7, v4
	v_mov_b32_e32 v12, v4
	v_mov_b32_e32 v13, v4
	v_mov_b32_e32 v14, v4
	v_mov_b32_e32 v15, v4
	v_mov_b32_e32 v20, v4
	v_mov_b32_e32 v21, v4
	v_mov_b32_e32 v22, v4
	v_mov_b32_e32 v23, v4
	v_mov_b32_e32 v28, v4
	v_mov_b32_e32 v29, v4
	v_mov_b32_e32 v30, v4
	v_mov_b32_e32 v31, v4
	v_mov_b32_e32 v36, v4
	v_mov_b32_e32 v37, v4
	v_mov_b32_e32 v38, v4
	v_mov_b32_e32 v39, v4
	v_mov_b32_e32 v44, v4
	v_mov_b32_e32 v45, v4
	v_mov_b32_e32 v46, v4
	v_mov_b32_e32 v47, v4
	v_mov_b32_e32 v52, v4
	v_mov_b32_e32 v53, v4
	v_mov_b32_e32 v54, v4
	v_mov_b32_e32 v55, v4
	v_mov_b32_e32 v60, v4
	v_mov_b32_e32 v61, v4
	v_mov_b32_e32 v62, v4
	v_mov_b32_e32 v63, v4
	v_mov_b32_e32 v8, v4
	v_mov_b32_e32 v9, v4
	v_mov_b32_e32 v10, v4
	v_mov_b32_e32 v11, v4
	v_mov_b32_e32 v16, v4
	v_mov_b32_e32 v17, v4
	v_mov_b32_e32 v18, v4
	v_mov_b32_e32 v19, v4
	v_mov_b32_e32 v24, v4
	v_mov_b32_e32 v25, v4
	v_mov_b32_e32 v26, v4
	v_mov_b32_e32 v27, v4
	v_mov_b32_e32 v32, v4
	v_mov_b32_e32 v33, v4
	v_mov_b32_e32 v34, v4
	v_mov_b32_e32 v35, v4
	v_mov_b32_e32 v40, v4
	v_mov_b32_e32 v41, v4
	v_mov_b32_e32 v42, v4
	v_mov_b32_e32 v43, v4
	v_mov_b32_e32 v48, v4
	v_mov_b32_e32 v49, v4
	v_mov_b32_e32 v50, v4
	v_mov_b32_e32 v51, v4
	v_mov_b32_e32 v56, v4
	v_mov_b32_e32 v57, v4
	v_mov_b32_e32 v58, v4
	v_mov_b32_e32 v59, v4
	v_mov_b32_e32 v64, v4
	v_mov_b32_e32 v65, v4
	v_mov_b32_e32 v66, v4
	v_mov_b32_e32 v67, v4
	v_mov_b32_e32 v68, v4
	v_mov_b32_e32 v69, v4
	v_mov_b32_e32 v70, v4
	v_mov_b32_e32 v71, v4
	v_mov_b32_e32 v76, v4
	v_mov_b32_e32 v77, v4
	v_mov_b32_e32 v78, v4
	v_mov_b32_e32 v79, v4
	v_mov_b32_e32 v84, v4
	v_mov_b32_e32 v85, v4
	v_mov_b32_e32 v86, v4
	v_mov_b32_e32 v87, v4
	v_mov_b32_e32 v92, v4
	v_mov_b32_e32 v93, v4
	v_mov_b32_e32 v94, v4
	v_mov_b32_e32 v95, v4
	v_mov_b32_e32 v100, v4
	v_mov_b32_e32 v101, v4
	v_mov_b32_e32 v102, v4
	v_mov_b32_e32 v103, v4
	v_mov_b32_e32 v108, v4
	v_mov_b32_e32 v109, v4
	v_mov_b32_e32 v110, v4
	v_mov_b32_e32 v111, v4
	v_mov_b32_e32 v116, v4
	v_mov_b32_e32 v117, v4
	v_mov_b32_e32 v118, v4
	v_mov_b32_e32 v119, v4
	v_mov_b32_e32 v124, v4
	v_mov_b32_e32 v125, v4
	v_mov_b32_e32 v126, v4
	v_mov_b32_e32 v127, v4
	v_mov_b32_e32 v72, v4
	v_mov_b32_e32 v73, v4
	v_mov_b32_e32 v74, v4
	v_mov_b32_e32 v75, v4
	v_mov_b32_e32 v80, v4
	v_mov_b32_e32 v81, v4
	v_mov_b32_e32 v82, v4
	v_mov_b32_e32 v83, v4
	v_mov_b32_e32 v88, v4
	v_mov_b32_e32 v89, v4
	v_mov_b32_e32 v90, v4
	v_mov_b32_e32 v91, v4
	v_mov_b32_e32 v96, v4
	v_mov_b32_e32 v97, v4
	v_mov_b32_e32 v98, v4
	v_mov_b32_e32 v99, v4
	v_mov_b32_e32 v104, v4
	v_mov_b32_e32 v105, v4
	v_mov_b32_e32 v106, v4
	v_mov_b32_e32 v107, v4
	v_mov_b32_e32 v112, v4
	v_mov_b32_e32 v113, v4
	v_mov_b32_e32 v114, v4
	v_mov_b32_e32 v115, v4
	v_mov_b32_e32 v120, v4
	v_mov_b32_e32 v121, v4
	v_mov_b32_e32 v122, v4
	v_mov_b32_e32 v123, v4
	v_mov_b32_e32 v128, v4
	v_mov_b32_e32 v129, v4
	v_mov_b32_e32 v130, v4
	v_mov_b32_e32 v131, v4
	v_readfirstlane_b32 s98, v151
	s_nop 3
	s_lshr_b32 s98, s98, 8
	s_cmp_lg_u32 s98, 0
	s_cbranch_scc0 .Lprio_skip_758
	s_setprio 1
.Lprio_skip_758:
.LBB0_758:
	s_add_u32 s22, s20, 0xfff80080
	s_addc_u32 s23, s21, -1
	s_add_i32 s48, 0, 0x10000
	v_add_u32_e32 v146, s48, v153
	ds_read_b128 v[174:177], v146
	ds_read_b128 v[178:181], v146 offset:1024
	ds_read_b128 v[182:185], v146 offset:2048
	ds_read_b128 v[186:189], v146 offset:3072
	s_cmp_eq_u32 s47, 28
	s_cselect_b32 s25, s15, s23
	s_cselect_b32 s24, s42, s22
	s_cselect_b32 s23, s13, s46
	s_cselect_b32 s22, s43, s44
	v_lshl_add_u64 v[146:147], s[20:21], 0, v[142:143]
	s_add_i32 m0, s33, 0xc000
	ds_read_b128 v[190:193], v172
	ds_read_b128 v[194:197], v172 offset:1024
	ds_read_b128 v[198:201], v172 offset:2048
	ds_read_b128 v[214:217], v172 offset:3072
	ds_read_b128 v[218:221], v172 offset:4096
	ds_read_b128 v[222:225], v172 offset:5120
	ds_read_b128 v[226:229], v172 offset:6144
	ds_read_b128 v[230:233], v172 offset:7168
	global_load_lds_dwordx4 v[146:147], off
	v_lshl_add_u64 v[146:147], s[20:21], 0, v[144:145]
	s_add_i32 m0, s33, 0xe000
	s_nop 0
	global_load_lds_dwordx4 v[146:147], off
	s_waitcnt lgkmcnt(8)
	s_barrier
	s_waitcnt lgkmcnt(0)
	s_waitcnt lgkmcnt(0)
	v_mfma_f32_16x16x32_bf16 v[128:131], v[174:177], v[190:193], v[128:131]
	v_mfma_f32_16x16x32_bf16 v[120:123], v[182:185], v[190:193], v[120:123]
	v_mfma_f32_16x16x32_bf16 v[112:115], v[174:177], v[198:201], v[112:115]
	v_mfma_f32_16x16x32_bf16 v[104:107], v[182:185], v[198:201], v[104:107]
	v_mfma_f32_16x16x32_bf16 v[96:99], v[174:177], v[218:221], v[96:99]
	v_mfma_f32_16x16x32_bf16 v[88:91], v[182:185], v[218:221], v[88:91]
	v_mfma_f32_16x16x32_bf16 v[80:83], v[174:177], v[226:229], v[80:83]
	v_mfma_f32_16x16x32_bf16 v[72:75], v[182:185], v[226:229], v[72:75]
	v_mfma_f32_16x16x32_bf16 v[128:131], v[178:181], v[194:197], v[128:131]
	v_mfma_f32_16x16x32_bf16 v[120:123], v[186:189], v[194:197], v[120:123]
	v_mfma_f32_16x16x32_bf16 v[112:115], v[178:181], v[214:217], v[112:115]
	v_mfma_f32_16x16x32_bf16 v[104:107], v[186:189], v[214:217], v[104:107]
	v_mfma_f32_16x16x32_bf16 v[96:99], v[178:181], v[222:225], v[96:99]
	v_mfma_f32_16x16x32_bf16 v[88:91], v[186:189], v[222:225], v[88:91]
	v_mfma_f32_16x16x32_bf16 v[80:83], v[178:181], v[230:233], v[80:83]
	v_mfma_f32_16x16x32_bf16 v[72:75], v[186:189], v[230:233], v[72:75]
	s_barrier
; #define PG8_STAGE(bufoff, gbase, voff) do { _Pragma("unroll") for (int _i = 0; _i < 2; ++_i) \
;         __builtin_amdgcn_global_load_lds((const unsigned*)((const char*)(gbase) + (voff)[_i]), (LAS unsigned*)(lds + (bufoff) + ldsw + _i * 8192), 16, 0, 0); } while (0)
; #define PG8_LDA(dst, b, h) do { _Pragma("unroll") for (int m = 0; m < 4; ++m) _Pragma("unroll") for (int k = 0; k < 2; ++k) dst[m][k] = *(const LAS bf16x8*)(lds + PG8_SA(b, h) + aoff + m * 2048 + k * 1024); } while (0)
; #define PG8_LDB(dst, b, h) do { _Pragma("unroll") for (int n = 0; n < 2; ++n) _Pragma("unroll") for (int k = 0; k < 2; ++k) dst[n][k] = *(const LAS bf16x8*)(lds + PG8_SB(b, h) + boff + n * 2048 + k * 1024); } while (0)
; #define PG8_MMA(ai, bj, At, Bt) do { __builtin_amdgcn_s_setprio(1); _Pragma("unroll") for (int m = 0; m < 4; ++m) _Pragma("unroll") for (int n = 0; n < 2; ++n) _Pragma("unroll") for (int k = 0; k < 2; ++k) \
;         acc[ai][bj][m][n] = __builtin_amdgcn_mfma_f32_16x16x32_bf16(Bt[n][k], At[m][k], acc[ai][bj][m][n], 0, 0, 0); __builtin_amdgcn_s_setprio(0); } while (0)
; #define PG8_WAIT_V(n) asm volatile("s_waitcnt vmcnt(" #n ")" ::: "memory")
; #define PG8_WAIT_L(n) asm volatile("s_waitcnt lgkmcnt(" #n ")" ::: "memory")
; #define PG8_BAR __builtin_amdgcn_s_barrier()
; #define PG8_SCHED __builtin_amdgcn_sched_barrier(0)
; template <class Epi>
; __device__ __forceinline__ void gemm_phase(LAS unsigned char* lds, const Gemm g, const StaticOrder& S, const Epi& E) {
;     ...
;             PG8_LDB(B1, 0, 1); PG8_STAGE(PG8_SB(0, 0), b2, voffB);
;             PG8_BAR; PG8_WAIT_L(0); PG8_MMA(0, 1, At, B1); PG8_BAR;
;             PG8_LDA(At, 0, 1); PG8_STAGE(PG8_SA(0, 0), a2, voffA);
;             PG8_BAR; PG8_WAIT_L(0); PG8_MMA(1, 0, At, B0); PG8_BAR; PG8_SCHED;
;             PG8_STAGE(PG8_SB(0, 1), b2 + hstep, voffB);
;             PG8_WAIT_V(6); PG8_BAR; PG8_MMA(1, 1, At, B1); PG8_BAR;
;             PG8_LDB(B0, 1, 0); PG8_SCHED; PG8_LDA(At, 1, 0); PG8_STAGE(PG8_SA(0, 1), a2 + hstep, voffA);
;             PG8_WAIT_L(8); PG8_BAR; PG8_WAIT_L(0); PG8_MMA(0, 0, At, B0); PG8_BAR; PG8_SCHED;
	s_add_i32 s52, 0, 0x14000
	v_add_u32_e32 v146, s52, v153
	s_add_i32 s48, s48, s30
	ds_read_b128 v[234:237], v146
	ds_read_b128 v[238:241], v146 offset:1024
	ds_read_b128 v[242:245], v146 offset:2048
	ds_read_b128 v[246:249], v146 offset:3072
	v_lshl_add_u64 v[146:147], s[22:23], 0, v[136:137]
	s_mov_b32 m0, s48
	v_lshl_add_u64 v[170:171], s[22:23], 0, v[132:133]
	global_load_lds_dwordx4 v[146:147], off
	s_add_i32 m0, s48, 0x2000
	s_nop 0
	global_load_lds_dwordx4 v[170:171], off
	s_barrier
	s_waitcnt lgkmcnt(0)
	s_waitcnt lgkmcnt(0)
	v_mfma_f32_16x16x32_bf16 v[124:127], v[234:237], v[190:193], v[124:127]
	v_mfma_f32_16x16x32_bf16 v[116:119], v[242:245], v[190:193], v[116:119]
	v_mfma_f32_16x16x32_bf16 v[108:111], v[234:237], v[198:201], v[108:111]
	v_mfma_f32_16x16x32_bf16 v[100:103], v[242:245], v[198:201], v[100:103]
	v_mfma_f32_16x16x32_bf16 v[92:95], v[234:237], v[218:221], v[92:95]
	v_mfma_f32_16x16x32_bf16 v[84:87], v[242:245], v[218:221], v[84:87]
	v_mfma_f32_16x16x32_bf16 v[76:79], v[234:237], v[226:229], v[76:79]
	v_mfma_f32_16x16x32_bf16 v[68:71], v[242:245], v[226:229], v[68:71]
	v_mfma_f32_16x16x32_bf16 v[124:127], v[238:241], v[194:197], v[124:127]
	v_mfma_f32_16x16x32_bf16 v[116:119], v[246:249], v[194:197], v[116:119]
	v_mfma_f32_16x16x32_bf16 v[108:111], v[238:241], v[214:217], v[108:111]
	v_mfma_f32_16x16x32_bf16 v[100:103], v[246:249], v[214:217], v[100:103]
	v_mfma_f32_16x16x32_bf16 v[92:95], v[238:241], v[222:225], v[92:95]
	v_mfma_f32_16x16x32_bf16 v[84:87], v[246:249], v[222:225], v[84:87]
	v_mfma_f32_16x16x32_bf16 v[76:79], v[238:241], v[230:233], v[76:79]
	v_mfma_f32_16x16x32_bf16 v[68:71], v[246:249], v[230:233], v[68:71]
	s_mov_b32 m0, s33
	v_lshl_add_u64 v[250:251], s[24:25], 0, v[138:139]
	s_barrier
	ds_read_b128 v[190:193], v172 offset:16384
	ds_read_b128 v[194:197], v172 offset:17408
	ds_read_b128 v[198:201], v172 offset:18432
	ds_read_b128 v[214:217], v172 offset:19456
	ds_read_b128 v[218:221], v172 offset:20480
	ds_read_b128 v[222:225], v172 offset:21504
	ds_read_b128 v[226:229], v172 offset:22528
	ds_read_b128 v[230:233], v172 offset:23552
	global_load_lds_dwordx4 v[250:251], off
	v_lshl_add_u64 v[252:253], s[24:25], 0, v[134:135]
	s_mov_b32 m0, s36
	s_nop 0
	global_load_lds_dwordx4 v[252:253], off
	s_barrier
	s_waitcnt lgkmcnt(0)
	s_waitcnt lgkmcnt(0)
	v_mfma_f32_16x16x32_bf16 v[64:67], v[174:177], v[190:193], v[64:67]
	v_mfma_f32_16x16x32_bf16 v[56:59], v[182:185], v[190:193], v[56:59]
	v_mfma_f32_16x16x32_bf16 v[48:51], v[174:177], v[198:201], v[48:51]
	v_mfma_f32_16x16x32_bf16 v[40:43], v[182:185], v[198:201], v[40:43]
	v_mfma_f32_16x16x32_bf16 v[32:35], v[174:177], v[218:221], v[32:35]
	v_mfma_f32_16x16x32_bf16 v[24:27], v[182:185], v[218:221], v[24:27]
	v_mfma_f32_16x16x32_bf16 v[16:19], v[174:177], v[226:229], v[16:19]
	v_mfma_f32_16x16x32_bf16 v[8:11], v[182:185], v[226:229], v[8:11]
	v_mfma_f32_16x16x32_bf16 v[64:67], v[178:181], v[194:197], v[64:67]
	v_mfma_f32_16x16x32_bf16 v[56:59], v[186:189], v[194:197], v[56:59]
	v_mfma_f32_16x16x32_bf16 v[48:51], v[178:181], v[214:217], v[48:51]
	v_mfma_f32_16x16x32_bf16 v[40:43], v[186:189], v[214:217], v[40:43]
	v_mfma_f32_16x16x32_bf16 v[32:35], v[178:181], v[222:225], v[32:35]
	v_mfma_f32_16x16x32_bf16 v[24:27], v[186:189], v[222:225], v[24:27]
	v_mfma_f32_16x16x32_bf16 v[16:19], v[178:181], v[230:233], v[16:19]
	v_mfma_f32_16x16x32_bf16 v[8:11], v[186:189], v[230:233], v[8:11]
	s_barrier
	s_add_u32 s72, s22, 0x80000
	s_addc_u32 s73, s23, 0
	s_add_i32 s48, s52, s30
	v_lshl_add_u64 v[174:175], s[72:73], 0, v[136:137]
	s_mov_b32 m0, s48
	s_nop 0
	global_load_lds_dwordx4 v[174:175], off
	v_lshl_add_u64 v[174:175], s[72:73], 0, v[132:133]
	s_add_i32 m0, s48, 0x2000
	s_nop 0
	global_load_lds_dwordx4 v[174:175], off
	s_waitcnt vmcnt(6)
	s_barrier
	v_mfma_f32_16x16x32_bf16 v[60:63], v[234:237], v[190:193], v[60:63]
	v_mfma_f32_16x16x32_bf16 v[52:55], v[242:245], v[190:193], v[52:55]
	v_mfma_f32_16x16x32_bf16 v[44:47], v[234:237], v[198:201], v[44:47]
	v_mfma_f32_16x16x32_bf16 v[36:39], v[242:245], v[198:201], v[36:39]
	v_mfma_f32_16x16x32_bf16 v[28:31], v[234:237], v[218:221], v[28:31]
	v_mfma_f32_16x16x32_bf16 v[20:23], v[242:245], v[218:221], v[20:23]
	v_mfma_f32_16x16x32_bf16 v[12:15], v[234:237], v[226:229], v[12:15]
	v_mfma_f32_16x16x32_bf16 v[4:7], v[242:245], v[226:229], v[4:7]
	v_mfma_f32_16x16x32_bf16 v[60:63], v[238:241], v[194:197], v[60:63]
	v_mfma_f32_16x16x32_bf16 v[52:55], v[246:249], v[194:197], v[52:55]
	v_mfma_f32_16x16x32_bf16 v[44:47], v[238:241], v[214:217], v[44:47]
	v_mfma_f32_16x16x32_bf16 v[36:39], v[246:249], v[214:217], v[36:39]
	v_mfma_f32_16x16x32_bf16 v[28:31], v[238:241], v[222:225], v[28:31]
	v_mfma_f32_16x16x32_bf16 v[20:23], v[246:249], v[222:225], v[20:23]
	v_mfma_f32_16x16x32_bf16 v[12:15], v[238:241], v[230:233], v[12:15]
	v_mfma_f32_16x16x32_bf16 v[4:7], v[246:249], v[230:233], v[4:7]
	s_add_i32 s48, 0, 0x18000
	v_add_u32_e32 v148, s48, v153
	s_barrier
	ds_read_b128 v[174:177], v148
	ds_read_b128 v[178:181], v148 offset:1024
	ds_read_b128 v[182:185], v148 offset:2048
	ds_read_b128 v[186:189], v148 offset:3072
	s_add_u32 s24, s24, 0x80000
	s_addc_u32 s25, s25, 0
	s_mov_b32 m0, s37
	v_lshl_add_u64 v[234:235], s[24:25], 0, v[138:139]
	ds_read_b128 v[190:193], v172 offset:32768
	ds_read_b128 v[194:197], v172 offset:33792
	ds_read_b128 v[198:201], v172 offset:34816
	ds_read_b128 v[214:217], v172 offset:35840
	ds_read_b128 v[218:221], v172 offset:36864
	ds_read_b128 v[222:225], v172 offset:37888
	ds_read_b128 v[226:229], v172 offset:38912
	ds_read_b128 v[230:233], v172 offset:39936
	global_load_lds_dwordx4 v[234:235], off
	v_lshl_add_u64 v[234:235], s[24:25], 0, v[134:135]
	s_mov_b32 m0, s38
	s_nop 0
	global_load_lds_dwordx4 v[234:235], off
	s_waitcnt lgkmcnt(8)
	s_barrier
; #define PG8_STAGE(bufoff, gbase, voff) do { _Pragma("unroll") for (int _i = 0; _i < 2; ++_i) \
;         __builtin_amdgcn_global_load_lds((const unsigned*)((const char*)(gbase) + (voff)[_i]), (LAS unsigned*)(lds + (bufoff) + ldsw + _i * 8192), 16, 0, 0); } while (0)
; #define PG8_LDA(dst, b, h) do { _Pragma("unroll") for (int m = 0; m < 4; ++m) _Pragma("unroll") for (int k = 0; k < 2; ++k) dst[m][k] = *(const LAS bf16x8*)(lds + PG8_SA(b, h) + aoff + m * 2048 + k * 1024); } while (0)
; #define PG8_LDB(dst, b, h) do { _Pragma("unroll") for (int n = 0; n < 2; ++n) _Pragma("unroll") for (int k = 0; k < 2; ++k) dst[n][k] = *(const LAS bf16x8*)(lds + PG8_SB(b, h) + boff + n * 2048 + k * 1024); } while (0)
; #define PG8_MMA(ai, bj, At, Bt) do { __builtin_amdgcn_s_setprio(1); _Pragma("unroll") for (int m = 0; m < 4; ++m) _Pragma("unroll") for (int n = 0; n < 2; ++n) _Pragma("unroll") for (int k = 0; k < 2; ++k) \
;         acc[ai][bj][m][n] = __builtin_amdgcn_mfma_f32_16x16x32_bf16(Bt[n][k], At[m][k], acc[ai][bj][m][n], 0, 0, 0); __builtin_amdgcn_s_setprio(0); } while (0)
; #define PG8_WAIT_L(n) asm volatile("s_waitcnt lgkmcnt(" #n ")" ::: "memory")
; #define PG8_BAR __builtin_amdgcn_s_barrier()
; #define PG8_SCHED __builtin_amdgcn_sched_barrier(0)
; template <class Epi>
; __device__ __forceinline__ void gemm_phase(LAS unsigned char* lds, const Gemm g, const StaticOrder& S, const Epi& E) {
;     ...
;             PG8_WAIT_L(8); PG8_BAR; PG8_WAIT_L(0); PG8_MMA(0, 0, At, B0); PG8_BAR; PG8_SCHED;
;             PG8_LDB(B1, 1, 1); PG8_STAGE(PG8_SB(1, 0), b3, voffB);
;             PG8_BAR; PG8_WAIT_L(0); PG8_MMA(0, 1, At, B1); PG8_BAR;
;             PG8_LDA(At, 1, 1); PG8_STAGE(PG8_SA(1, 0), a3, voffA);
	s_waitcnt lgkmcnt(0)
	s_waitcnt lgkmcnt(0)
	v_mfma_f32_16x16x32_bf16 v[128:131], v[174:177], v[190:193], v[128:131]
	v_mfma_f32_16x16x32_bf16 v[120:123], v[182:185], v[190:193], v[120:123]
	v_mfma_f32_16x16x32_bf16 v[112:115], v[174:177], v[198:201], v[112:115]
	v_mfma_f32_16x16x32_bf16 v[104:107], v[182:185], v[198:201], v[104:107]
	v_mfma_f32_16x16x32_bf16 v[96:99], v[174:177], v[218:221], v[96:99]
	v_mfma_f32_16x16x32_bf16 v[88:91], v[182:185], v[218:221], v[88:91]
	v_mfma_f32_16x16x32_bf16 v[80:83], v[174:177], v[226:229], v[80:83]
	v_mfma_f32_16x16x32_bf16 v[72:75], v[182:185], v[226:229], v[72:75]
	v_mfma_f32_16x16x32_bf16 v[128:131], v[178:181], v[194:197], v[128:131]
	v_mfma_f32_16x16x32_bf16 v[120:123], v[186:189], v[194:197], v[120:123]
	v_mfma_f32_16x16x32_bf16 v[112:115], v[178:181], v[214:217], v[112:115]
	v_mfma_f32_16x16x32_bf16 v[104:107], v[186:189], v[214:217], v[104:107]
	v_mfma_f32_16x16x32_bf16 v[96:99], v[178:181], v[222:225], v[96:99]
	v_mfma_f32_16x16x32_bf16 v[88:91], v[186:189], v[222:225], v[88:91]
	v_mfma_f32_16x16x32_bf16 v[80:83], v[178:181], v[230:233], v[80:83]
	v_mfma_f32_16x16x32_bf16 v[72:75], v[186:189], v[230:233], v[72:75]
	s_barrier
	s_add_i32 s24, 0, 0x1c000
	s_add_i32 s25, s48, s30
	v_add_u32_e32 v148, s24, v153
	v_lshl_add_u64 v[146:147], v[146:147], 0, s[34:35]
	s_mov_b32 m0, s25
	ds_read_b128 v[234:237], v148
	ds_read_b128 v[238:241], v148 offset:1024
	ds_read_b128 v[242:245], v148 offset:2048
	ds_read_b128 v[246:249], v148 offset:3072
	global_load_lds_dwordx4 v[146:147], off
	v_lshl_add_u64 v[146:147], v[170:171], 0, s[34:35]
	s_add_i32 m0, s25, 0x2000
	s_nop 0
	global_load_lds_dwordx4 v[146:147], off
	s_barrier
	s_waitcnt lgkmcnt(0)
	s_waitcnt lgkmcnt(0)
	v_mfma_f32_16x16x32_bf16 v[124:127], v[234:237], v[190:193], v[124:127]
	v_mfma_f32_16x16x32_bf16 v[116:119], v[242:245], v[190:193], v[116:119]
	v_mfma_f32_16x16x32_bf16 v[108:111], v[234:237], v[198:201], v[108:111]
	v_mfma_f32_16x16x32_bf16 v[100:103], v[242:245], v[198:201], v[100:103]
	v_mfma_f32_16x16x32_bf16 v[92:95], v[234:237], v[218:221], v[92:95]
	v_mfma_f32_16x16x32_bf16 v[84:87], v[242:245], v[218:221], v[84:87]
	v_mfma_f32_16x16x32_bf16 v[76:79], v[234:237], v[226:229], v[76:79]
	v_mfma_f32_16x16x32_bf16 v[68:71], v[242:245], v[226:229], v[68:71]
	v_mfma_f32_16x16x32_bf16 v[124:127], v[238:241], v[194:197], v[124:127]
	v_mfma_f32_16x16x32_bf16 v[116:119], v[246:249], v[194:197], v[116:119]
	v_mfma_f32_16x16x32_bf16 v[108:111], v[238:241], v[214:217], v[108:111]
	v_mfma_f32_16x16x32_bf16 v[100:103], v[246:249], v[214:217], v[100:103]
	v_mfma_f32_16x16x32_bf16 v[92:95], v[238:241], v[222:225], v[92:95]
	v_mfma_f32_16x16x32_bf16 v[84:87], v[246:249], v[222:225], v[84:87]
	v_mfma_f32_16x16x32_bf16 v[76:79], v[238:241], v[230:233], v[76:79]
	v_mfma_f32_16x16x32_bf16 v[68:71], v[246:249], v[230:233], v[68:71]
	s_mov_b32 m0, s39
	v_lshl_add_u64 v[146:147], v[250:251], 0, s[34:35]
	s_barrier
	ds_read_b128 v[190:193], v172 offset:49152
	ds_read_b128 v[194:197], v172 offset:50176
	ds_read_b128 v[198:201], v172 offset:51200
	ds_read_b128 v[214:217], v172 offset:52224
	ds_read_b128 v[218:221], v172 offset:53248
	ds_read_b128 v[222:225], v172 offset:54272
	ds_read_b128 v[226:229], v172 offset:55296
	ds_read_b128 v[230:233], v172 offset:56320
	global_load_lds_dwordx4 v[146:147], off
	v_lshl_add_u64 v[146:147], v[252:253], 0, s[34:35]
	s_mov_b32 m0, s40
	s_nop 0
	global_load_lds_dwordx4 v[146:147], off
	s_barrier
; __device__ __forceinline__ unsigned pack2(float lo, float hi) { unsigned r; asm("v_cvt_pk_bf16_f32 %0, %1, %2" : "=v"(r) : "v"(lo), "v"(hi)); return r; }
; #define PG8_STAGE(bufoff, gbase, voff) do { _Pragma("unroll") for (int _i = 0; _i < 2; ++_i) \
;         __builtin_amdgcn_global_load_lds((const unsigned*)((const char*)(gbase) + (voff)[_i]), (LAS unsigned*)(lds + (bufoff) + ldsw + _i * 8192), 16, 0, 0); } while (0)
; #define PG8_MMA(ai, bj, At, Bt) do { __builtin_amdgcn_s_setprio(1); _Pragma("unroll") for (int m = 0; m < 4; ++m) _Pragma("unroll") for (int n = 0; n < 2; ++n) _Pragma("unroll") for (int k = 0; k < 2; ++k) \
;         acc[ai][bj][m][n] = __builtin_amdgcn_mfma_f32_16x16x32_bf16(Bt[n][k], At[m][k], acc[ai][bj][m][n], 0, 0, 0); __builtin_amdgcn_s_setprio(0); } while (0)
; #define PG8_WAIT_V(n) asm volatile("s_waitcnt vmcnt(" #n ")" ::: "memory")
; template <class Epi>
; __device__ __forceinline__ void gemm_phase(LAS unsigned char* lds, const Gemm g, const StaticOrder& S, const Epi& E) {
;     ...
;             PG8_BAR; PG8_WAIT_L(0); PG8_MMA(1, 0, At, B0); PG8_BAR; PG8_SCHED;
;             PG8_STAGE(PG8_SB(1, 1), b3 + hstep, voffB);
;             PG8_WAIT_V(6); PG8_BAR; PG8_MMA(1, 1, At, B1); PG8_BAR;
;     __device__ __forceinline__ void operator()(const AccT& acc, const pg8::Unit& u, int wr, int wc, int fr, int fq) const {
;         const int row0 = u.pm * 256 + wr * 64 + fr, col0 = u.pn * 256 + wc * 32 + 8 * fq;
;         const bool side_dt = (u.pn == 18 && wc == 0), side_if = (u.pn == 34 && wc == 1);
; #pragma unroll
;         for (int ai = 0; ai < 2; ++ai)
; #pragma unroll
;             for (int m = 0; m < 4; ++m) {
;                 const int row = row0 + ai * 128 + m * 16;
;                 bf16_t* rowp = U + (size_t)row * N1P + col0;
; #pragma unroll
;                 for (int bj = 0; bj < 2; ++bj) {
;                     const f32x4 v0 = acc[ai][bj][m][0], v1 = acc[ai][bj][m][1];
;                     u32x4 o; o[0] = pack2(v0[0], v0[1]); o[1] = pack2(v0[2], v0[3]); o[2] = pack2(v1[0], v1[1]); o[3] = pack2(v1[2], v1[3]);
;                     *(u32x4*)(rowp + bj * 128) = o;
;                 }
;                 if (side_dt || side_if) {
;                     float* sp = sf + (size_t)row * 64 + (side_if ? 32 : 0) + 8 * fq;
;                     *(f32x4*)sp = acc[ai][0][m][0]; *(f32x4*)(sp + 4) = acc[ai][0][m][1];
;                 }
	s_waitcnt lgkmcnt(0)
	s_waitcnt lgkmcnt(0)
	v_mfma_f32_16x16x32_bf16 v[64:67], v[174:177], v[190:193], v[64:67]
	v_mfma_f32_16x16x32_bf16 v[56:59], v[182:185], v[190:193], v[56:59]
	v_mfma_f32_16x16x32_bf16 v[48:51], v[174:177], v[198:201], v[48:51]
	v_mfma_f32_16x16x32_bf16 v[40:43], v[182:185], v[198:201], v[40:43]
	v_mfma_f32_16x16x32_bf16 v[32:35], v[174:177], v[218:221], v[32:35]
	v_mfma_f32_16x16x32_bf16 v[24:27], v[182:185], v[218:221], v[24:27]
	v_mfma_f32_16x16x32_bf16 v[16:19], v[174:177], v[226:229], v[16:19]
	v_mfma_f32_16x16x32_bf16 v[8:11], v[182:185], v[226:229], v[8:11]
	v_mfma_f32_16x16x32_bf16 v[64:67], v[178:181], v[194:197], v[64:67]
	v_mfma_f32_16x16x32_bf16 v[56:59], v[186:189], v[194:197], v[56:59]
	v_mfma_f32_16x16x32_bf16 v[48:51], v[178:181], v[214:217], v[48:51]
	v_mfma_f32_16x16x32_bf16 v[40:43], v[186:189], v[214:217], v[40:43]
	v_mfma_f32_16x16x32_bf16 v[32:35], v[178:181], v[222:225], v[32:35]
	v_mfma_f32_16x16x32_bf16 v[24:27], v[186:189], v[222:225], v[24:27]
	v_mfma_f32_16x16x32_bf16 v[16:19], v[178:181], v[230:233], v[16:19]
	v_mfma_f32_16x16x32_bf16 v[8:11], v[186:189], v[230:233], v[8:11]
	s_barrier
	s_add_u32 s22, s22, 0x80080
	s_addc_u32 s23, s23, 0
	s_add_i32 s24, s24, s30
	v_lshl_add_u64 v[146:147], s[22:23], 0, v[136:137]
	s_mov_b32 m0, s24
	s_nop 0
	global_load_lds_dwordx4 v[146:147], off
	v_lshl_add_u64 v[146:147], s[22:23], 0, v[132:133]
	s_add_i32 m0, s24, 0x2000
	s_nop 0
	global_load_lds_dwordx4 v[146:147], off
	s_waitcnt vmcnt(6)
	s_barrier
	v_mfma_f32_16x16x32_bf16 v[60:63], v[234:237], v[190:193], v[60:63]
	v_mfma_f32_16x16x32_bf16 v[52:55], v[242:245], v[190:193], v[52:55]
	v_mfma_f32_16x16x32_bf16 v[44:47], v[234:237], v[198:201], v[44:47]
	v_mfma_f32_16x16x32_bf16 v[36:39], v[242:245], v[198:201], v[36:39]
	v_mfma_f32_16x16x32_bf16 v[28:31], v[234:237], v[218:221], v[28:31]
	v_mfma_f32_16x16x32_bf16 v[20:23], v[242:245], v[218:221], v[20:23]
	v_mfma_f32_16x16x32_bf16 v[12:15], v[234:237], v[226:229], v[12:15]
	v_mfma_f32_16x16x32_bf16 v[4:7], v[242:245], v[226:229], v[4:7]
	v_mfma_f32_16x16x32_bf16 v[60:63], v[238:241], v[194:197], v[60:63]
	v_mfma_f32_16x16x32_bf16 v[52:55], v[246:249], v[194:197], v[52:55]
	v_mfma_f32_16x16x32_bf16 v[44:47], v[238:241], v[214:217], v[44:47]
	v_mfma_f32_16x16x32_bf16 v[36:39], v[246:249], v[214:217], v[36:39]
	v_mfma_f32_16x16x32_bf16 v[28:31], v[238:241], v[222:225], v[28:31]
	v_mfma_f32_16x16x32_bf16 v[20:23], v[246:249], v[222:225], v[20:23]
	v_mfma_f32_16x16x32_bf16 v[12:15], v[238:241], v[230:233], v[12:15]
	v_mfma_f32_16x16x32_bf16 v[4:7], v[246:249], v[230:233], v[4:7]
	s_add_i32 s47, s47, 2
	s_add_u32 s20, s20, 0x100
	s_addc_u32 s21, s21, 0
	s_add_u32 s44, s44, 0x100
	s_addc_u32 s46, s46, 0
	s_cmp_gt_u32 s47, 29
	s_barrier
	s_cbranch_scc0 .LBB0_758
	s_setprio 0
	s_cmp_eq_u32 s5, 18
	s_cselect_b64 s[20:21], -1, 0
	s_and_b64 s[20:21], s[8:9], s[20:21]
	s_cmp_eq_u32 s5, 34
	v_lshl_add_u32 v170, s4, 8, v141
	v_lshl_or_b32 v146, s5, 8, v163
	s_cselect_b64 s[4:5], -1, 0
	s_and_b64 s[4:5], s[10:11], s[4:5]
	s_or_b64 s[20:21], s[20:21], s[4:5]
	v_mov_b64_e32 v[174:175], s[2:3]
	v_ashrrev_i32_e32 v147, 31, v146
	s_and_b64 s[4:5], s[4:5], exec
	v_mad_i64_i32 v[174:175], s[4:5], v170, s45, v[174:175]
	v_cvt_pk_bf16_f32 v124, v124, v125
	v_cvt_pk_bf16_f32 v125, v126, v127
	v_cvt_pk_bf16_f32 v126, v116, v117
	v_cndmask_b32_e64 v116, 0, 1, s[20:21]
	s_cselect_b32 s13, 32, 0
	v_ashrrev_i32_e32 v171, 31, v170
	v_lshl_add_u64 v[178:179], v[146:147], 1, v[174:175]
	v_cmp_ne_u32_e64 s[4:5], 1, v116
	s_andn2_b64 vcc, exec, s[20:21]
	v_lshlrev_b32_e32 v148, 2, v140
	v_cvt_pk_bf16_f32 v174, v128, v129
	v_cvt_pk_bf16_f32 v175, v130, v131
	v_cvt_pk_bf16_f32 v176, v120, v121
	v_cvt_pk_bf16_f32 v177, v122, v123
	global_store_dwordx4 v[178:179], v[174:177], off
	v_cvt_pk_bf16_f32 v127, v118, v119
	global_store_dwordx4 v[178:179], v[124:127], off offset:256
	s_cbranch_vccnz .LBB0_761
	v_lshlrev_b64 v[116:117], 8, v[170:171]
	v_lshl_add_u64 v[116:117], s[6:7], 0, v[116:117]
	s_lshl_b32 s96, s13, 2
	v_lshl_add_u64 v[116:117], v[116:117], 0, s[96:97]
	v_lshl_add_u64 v[116:117], v[116:117], 0, v[148:149]
	global_store_dwordx4 v[116:117], v[128:131], off
	global_store_dwordx4 v[116:117], v[120:123], off offset:16
